# adds: EpiKV/EpiQN epilogues load the per-lane norm gains once per unit instead of 16x/32x with a vmcnt(0) each (on top of P4 EpiResGate pipelined epilogue + attention DMA issue moved to waves 4-7)
# speedup vs baseline: 1.0087x; 1.0087x over previous
; #define PG8_LAS __attribute__((address_space(3)))
; __device__ __forceinline__ unsigned cvt_pk_bf16(float lo, float hi) { unsigned r; asm volatile("v_cvt_pk_bf16_f32 %0, %1, %2" : "=v"(r) : "v"(lo), "v"(hi)); return r; }
;     __device__ __forceinline__ void operator()(const f32x4 (&acc)[2][2][4][2], const Unit& u, int wr_, int wc_, int fr_, int fq_) const {
;     ...
;             for (int ai = 0; ai < 2; ++ai)
; #pragma unroll
;                 for (int m = 0; m < 4; ++m) { int rl = ai * HALF + wr * 64 + m * 16 + fr; asm volatile("" : "+v"(rl));
; #pragma unroll
;                     for (int bj = 0; bj < 2; ++bj) { const f32x4 pp = *(const PG8_LAS f32x4*)(P + (rl * 2 + bj) * 4);
;                         const float rr = 1.0f / sqrtf(((pp[0] + pp[1]) + (pp[2] + pp[3])) * (1.0f / 128.0f) + RMS_EPS_F);
;                         const int head = 2 * u.pn + bj;
;                         const unsigned qoff = (unsigned)(((b * 4 + head) * 8192 + s0 + rl) * 192 + wc * 32 + 8 * fq); u32x4 w;
; #pragma unroll
;                         for (int n = 0; n < 2; ++n) { const f32x4 g = *(const f32x4*)(gn_nope + wc * 32 + 8 * fq + 4 * n);
;                             const f32x4 v = acc[ai][bj][m][n] * rr * g; w[2 * n] = cvt_pk_bf16(v[0], v[1]); w[2 * n + 1] = cvt_pk_bf16(v[2], v[3]); }
;                         *(u32x4*)(Q + qoff) = w; }
.LBB0_409:
	s_or_b64 exec, exec, s[0:1]
	v_lshl_or_b32 v146, v144, 6, v140
	v_mov_b32_e32 v144, v146
	s_waitcnt lgkmcnt(0)
	s_barrier
	s_lshl_b32 s0, s45, 8
	v_lshl_add_u32 v154, v144, 5, s24
	ds_read_b128 v[148:151], v154
	s_and_b32 s25, s0, 0x1f00
	s_waitcnt lgkmcnt(0)
	v_add_u32_e32 v147, s25, v144
	s_mov_b32 s46, 0xf800000
	v_lshlrev_b32_e32 v160, 7, v143
	v_mov_b32_e32 v152, v149
	v_mov_b32_e32 v153, v150
	v_mov_b32_e32 v149, v151
	v_pk_add_f32 v[148:149], v[152:153], v[148:149]
	v_lshlrev_b32_e32 v140, 3, v142
	v_add_f32_e32 v144, v148, v149
	v_fmamk_f32 v144, v144, 0x3c000000, v199
	v_cmp_gt_f32_e32 vcc, s46, v144
	v_mul_f32_e32 v148, 0x4f800000, v144
	v_lshl_or_b32 v140, v143, 5, v140
	v_cndmask_b32_e32 v144, v144, v148, vcc
	v_sqrt_f32_e32 v148, v144
	s_nop 0
	v_add_u32_e32 v149, -1, v148
	v_fma_f32 v150, -v149, v148, v144
	v_cmp_ge_f32_e64 s[0:1], 0, v150
	v_add_u32_e32 v150, 1, v148
	s_nop 0
	v_cndmask_b32_e64 v149, v148, v149, s[0:1]
	v_fma_f32 v148, -v150, v148, v144
	v_cmp_lt_f32_e64 s[0:1], 0, v148
	s_nop 1
	v_cndmask_b32_e64 v148, v149, v150, s[0:1]
	v_mul_f32_e32 v149, 0x37800000, v148
	v_cndmask_b32_e32 v148, v148, v149, vcc
	v_cmp_class_f32_e32 vcc, v144, v201
	s_nop 1
	v_cndmask_b32_e32 v144, v148, v144, vcc
	v_div_scale_f32 v148, s[0:1], v144, v144, 1.0
	v_rcp_f32_e32 v149, v148
	s_lshl_b32 s1, s45, 10
	s_lshl_b32 s0, s33, 14
	s_and_b32 s26, s1, 0xffff8000
	v_fma_f32 v150, -v148, v149, 1.0
	v_fmac_f32_e32 v149, v150, v149
	v_div_scale_f32 v150, vcc, 1.0, v144, 1.0
	v_mul_f32_e32 v151, v150, v149
	v_fma_f32 v152, -v148, v151, v150
	v_fmac_f32_e32 v151, v152, v149
	v_fma_f32 v148, -v148, v151, v150
	v_div_fmas_f32 v148, v148, v149, v151
	v_div_fixup_f32 v144, v148, v144, 1.0
	v_lshl_add_u64 v[148:149], s[14:15], 0, v[160:161]
	v_lshlrev_b32_e32 v160, 5, v142
	v_lshl_add_u64 v[142:143], v[148:149], 0, v[160:161]
	global_load_dwordx4 v[228:231], v[142:143], off
	v_pk_mul_f32 v[124:125], v[124:125], v[144:145] op_sel_hi:[1,0]
	v_pk_mul_f32 v[126:127], v[126:127], v[144:145] op_sel_hi:[1,0]
	s_add_i32 s26, s26, s0
	v_pk_mul_f32 v[120:121], v[120:121], v[144:145] op_sel_hi:[1,0]
	v_add_u32_e32 v152, s26, v147
	s_movk_i32 s33, 0xc0
	v_pk_mul_f32 v[122:123], v[122:123], v[144:145] op_sel_hi:[1,0]
	s_or_b32 s27, s26, 0x2000
	s_waitcnt vmcnt(0)
	v_pk_mul_f32 v[124:125], v[228:229], v[124:125]
	v_pk_mul_f32 v[126:127], v[230:231], v[126:127]
	v_cvt_pk_bf16_f32 v124, v124, v125
	s_nop 0
	v_cvt_pk_bf16_f32 v125, v126, v127
	global_load_dwordx4 v[232:235], v[142:143], off offset:16
	s_waitcnt vmcnt(0)
	v_pk_mul_f32 v[120:121], v[232:233], v[120:121]
	s_nop 0
	v_cvt_pk_bf16_f32 v126, v120, v121
	v_mad_u64_u32 v[120:121], s[0:1], v152, s33, v[140:141]
	v_mov_b32_e32 v121, v161
	v_pk_mul_f32 v[122:123], v[234:235], v[122:123]
	v_lshl_add_u64 v[120:121], v[120:121], 1, s[62:63]
	v_cvt_pk_bf16_f32 v127, v122, v123
	global_store_dwordx4 v[120:121], v[124:127], off
	ds_read_b128 v[120:123], v154 offset:16
	s_waitcnt lgkmcnt(0)
	v_mov_b32_e32 v124, v121
	v_mov_b32_e32 v125, v122
	v_mov_b32_e32 v121, v123
	v_pk_add_f32 v[120:121], v[124:125], v[120:121]
	s_nop 0
	v_add_f32_e32 v120, v120, v121
	v_fmamk_f32 v120, v120, 0x3c000000, v199
	v_cmp_gt_f32_e32 vcc, s46, v120
	v_mul_f32_e32 v121, 0x4f800000, v120
	s_nop 0
	v_cndmask_b32_e32 v120, v120, v121, vcc
	v_sqrt_f32_e32 v121, v120
	s_nop 0
	v_add_u32_e32 v122, -1, v121
	v_fma_f32 v123, -v122, v121, v120
	v_cmp_ge_f32_e64 s[0:1], 0, v123
	v_add_u32_e32 v123, 1, v121
	s_nop 0
	v_cndmask_b32_e64 v122, v121, v122, s[0:1]
	v_fma_f32 v121, -v123, v121, v120
	v_cmp_lt_f32_e64 s[0:1], 0, v121
	s_nop 1
	v_cndmask_b32_e64 v121, v122, v123, s[0:1]
	v_mul_f32_e32 v122, 0x37800000, v121
	v_cndmask_b32_e32 v121, v121, v122, vcc
	v_cmp_class_f32_e32 vcc, v120, v201
	s_nop 1
	v_cndmask_b32_e32 v120, v121, v120, vcc
	v_div_scale_f32 v121, s[0:1], v120, v120, 1.0
	v_rcp_f32_e32 v122, v121
	s_nop 0
	v_fma_f32 v123, -v121, v122, 1.0
	v_fmac_f32_e32 v122, v123, v122
	v_div_scale_f32 v123, vcc, 1.0, v120, 1.0
	v_mul_f32_e32 v124, v123, v122
	v_fma_f32 v125, -v121, v124, v123
	v_fmac_f32_e32 v124, v125, v122
	v_fma_f32 v121, -v121, v124, v123
	v_div_fmas_f32 v121, v121, v122, v124
	v_div_fixup_f32 v120, v121, v120, 1.0
	v_add_u32_e32 v121, s27, v147
	v_pk_mul_f32 v[116:117], v[116:117], v[120:121] op_sel_hi:[1,0]
	v_pk_mul_f32 v[118:119], v[118:119], v[120:121] op_sel_hi:[1,0]
	v_pk_mul_f32 v[112:113], v[112:113], v[120:121] op_sel_hi:[1,0]
	v_pk_mul_f32 v[114:115], v[114:115], v[120:121] op_sel_hi:[1,0]
	v_pk_mul_f32 v[116:117], v[228:229], v[116:117]
	v_pk_mul_f32 v[118:119], v[230:231], v[118:119]
	v_cvt_pk_bf16_f32 v116, v116, v117
	s_nop 0
	v_cvt_pk_bf16_f32 v117, v118, v119
	v_pk_mul_f32 v[112:113], v[232:233], v[112:113]
	s_nop 0
	v_cvt_pk_bf16_f32 v118, v112, v113
	v_mad_u64_u32 v[112:113], s[0:1], v121, s33, v[140:141]
	v_mov_b32_e32 v113, v161
	v_lshl_add_u64 v[112:113], v[112:113], 1, s[62:63]
	v_pk_mul_f32 v[114:115], v[234:235], v[114:115]
	s_nop 0
	v_cvt_pk_bf16_f32 v119, v114, v115
	global_store_dwordx4 v[112:113], v[116:119], off
	v_or_b32_e32 v112, 16, v146
	s_nop 0
	v_lshl_add_u32 v119, v112, 5, s24
	v_add_u32_e32 v118, s25, v112
	ds_read_b128 v[112:115], v119
	s_waitcnt lgkmcnt(0)
; #define PG8_LAS __attribute__((address_space(3)))
; __device__ __forceinline__ unsigned cvt_pk_bf16(float lo, float hi) { unsigned r; asm volatile("v_cvt_pk_bf16_f32 %0, %1, %2" : "=v"(r) : "v"(lo), "v"(hi)); return r; }
;     __device__ __forceinline__ void operator()(const f32x4 (&acc)[2][2][4][2], const Unit& u, int wr_, int wc_, int fr_, int fq_) const {
;     ...
;             for (int ai = 0; ai < 2; ++ai)
; #pragma unroll
;                 for (int m = 0; m < 4; ++m) { int rl = ai * HALF + wr * 64 + m * 16 + fr; asm volatile("" : "+v"(rl));
; #pragma unroll
;                     for (int bj = 0; bj < 2; ++bj) { const f32x4 pp = *(const PG8_LAS f32x4*)(P + (rl * 2 + bj) * 4);
;                         const float rr = 1.0f / sqrtf(((pp[0] + pp[1]) + (pp[2] + pp[3])) * (1.0f / 128.0f) + RMS_EPS_F);
;                         const int head = 2 * u.pn + bj;
;                         const unsigned qoff = (unsigned)(((b * 4 + head) * 8192 + s0 + rl) * 192 + wc * 32 + 8 * fq); u32x4 w;
; #pragma unroll
;                         for (int n = 0; n < 2; ++n) { const f32x4 g = *(const f32x4*)(gn_nope + wc * 32 + 8 * fq + 4 * n);
;                             const f32x4 v = acc[ai][bj][m][n] * rr * g; w[2 * n] = cvt_pk_bf16(v[0], v[1]); w[2 * n + 1] = cvt_pk_bf16(v[2], v[3]); }
;                         *(u32x4*)(Q + qoff) = w; }
	v_mov_b32_e32 v116, v113
	v_mov_b32_e32 v117, v114
	v_mov_b32_e32 v113, v115
	v_pk_add_f32 v[112:113], v[116:117], v[112:113]
	s_nop 0
	v_add_f32_e32 v112, v112, v113
	v_fmamk_f32 v112, v112, 0x3c000000, v199
	v_cmp_gt_f32_e32 vcc, s46, v112
	v_mul_f32_e32 v113, 0x4f800000, v112
	s_nop 0
	v_cndmask_b32_e32 v112, v112, v113, vcc
	v_sqrt_f32_e32 v113, v112
	s_nop 0
	v_add_u32_e32 v114, -1, v113
	v_fma_f32 v115, -v114, v113, v112
	v_cmp_ge_f32_e64 s[0:1], 0, v115
	v_add_u32_e32 v115, 1, v113
	s_nop 0
	v_cndmask_b32_e64 v114, v113, v114, s[0:1]
	v_fma_f32 v113, -v115, v113, v112
	v_cmp_lt_f32_e64 s[0:1], 0, v113
	s_nop 1
	v_cndmask_b32_e64 v113, v114, v115, s[0:1]
	v_mul_f32_e32 v114, 0x37800000, v113
	v_cndmask_b32_e32 v113, v113, v114, vcc
	v_cmp_class_f32_e32 vcc, v112, v201
	s_nop 1
	v_cndmask_b32_e32 v112, v113, v112, vcc
	v_div_scale_f32 v113, s[0:1], v112, v112, 1.0
	v_rcp_f32_e32 v114, v113
	s_nop 0
	v_fma_f32 v115, -v113, v114, 1.0
	v_fmac_f32_e32 v114, v115, v114
	v_div_scale_f32 v115, vcc, 1.0, v112, 1.0
	v_mul_f32_e32 v116, v115, v114
	v_fma_f32 v117, -v113, v116, v115
	v_fmac_f32_e32 v116, v117, v114
	v_fma_f32 v113, -v113, v116, v115
	v_div_fmas_f32 v113, v113, v114, v116
	v_div_fixup_f32 v112, v113, v112, 1.0
	v_add_u32_e32 v113, s26, v118
	v_pk_mul_f32 v[108:109], v[108:109], v[112:113] op_sel_hi:[1,0]
	v_pk_mul_f32 v[110:111], v[110:111], v[112:113] op_sel_hi:[1,0]
	v_pk_mul_f32 v[104:105], v[104:105], v[112:113] op_sel_hi:[1,0]
	v_pk_mul_f32 v[106:107], v[106:107], v[112:113] op_sel_hi:[1,0]
	v_pk_mul_f32 v[108:109], v[228:229], v[108:109]
	v_pk_mul_f32 v[110:111], v[230:231], v[110:111]
	v_cvt_pk_bf16_f32 v108, v108, v109
	s_nop 0
	v_cvt_pk_bf16_f32 v109, v110, v111
	v_pk_mul_f32 v[104:105], v[232:233], v[104:105]
	s_nop 0
	v_cvt_pk_bf16_f32 v110, v104, v105
	v_mad_u64_u32 v[104:105], s[0:1], v113, s33, v[140:141]
	v_mov_b32_e32 v105, v161
	v_pk_mul_f32 v[106:107], v[234:235], v[106:107]
	v_lshl_add_u64 v[104:105], v[104:105], 1, s[62:63]
	v_cvt_pk_bf16_f32 v111, v106, v107
	global_store_dwordx4 v[104:105], v[108:111], off
	ds_read_b128 v[104:107], v119 offset:16
	s_waitcnt lgkmcnt(0)
	v_mov_b32_e32 v108, v105
	v_mov_b32_e32 v109, v106
	v_mov_b32_e32 v105, v107
	v_pk_add_f32 v[104:105], v[108:109], v[104:105]
	s_nop 0
	v_add_f32_e32 v104, v104, v105
	v_fmamk_f32 v104, v104, 0x3c000000, v199
	v_cmp_gt_f32_e32 vcc, s46, v104
	v_mul_f32_e32 v105, 0x4f800000, v104
	s_nop 0
	v_cndmask_b32_e32 v104, v104, v105, vcc
	v_sqrt_f32_e32 v105, v104
	s_nop 0
	v_add_u32_e32 v106, -1, v105
	v_fma_f32 v107, -v106, v105, v104
	v_cmp_ge_f32_e64 s[0:1], 0, v107
	v_add_u32_e32 v107, 1, v105
	s_nop 0
	v_cndmask_b32_e64 v106, v105, v106, s[0:1]
	v_fma_f32 v105, -v107, v105, v104
	v_cmp_lt_f32_e64 s[0:1], 0, v105
	s_nop 1
	v_cndmask_b32_e64 v105, v106, v107, s[0:1]
	v_mul_f32_e32 v106, 0x37800000, v105
	v_cndmask_b32_e32 v105, v105, v106, vcc
	v_cmp_class_f32_e32 vcc, v104, v201
	s_nop 1
	v_cndmask_b32_e32 v104, v105, v104, vcc
	v_div_scale_f32 v105, s[0:1], v104, v104, 1.0
	v_rcp_f32_e32 v106, v105
	s_nop 0
	v_fma_f32 v107, -v105, v106, 1.0
	v_fmac_f32_e32 v106, v107, v106
	v_div_scale_f32 v107, vcc, 1.0, v104, 1.0
	v_mul_f32_e32 v108, v107, v106
	v_fma_f32 v109, -v105, v108, v107
	v_fmac_f32_e32 v108, v109, v106
	v_fma_f32 v105, -v105, v108, v107
	v_div_fmas_f32 v105, v105, v106, v108
	v_div_fixup_f32 v104, v105, v104, 1.0
	v_add_u32_e32 v105, s27, v118
	v_pk_mul_f32 v[100:101], v[100:101], v[104:105] op_sel_hi:[1,0]
	v_pk_mul_f32 v[102:103], v[102:103], v[104:105] op_sel_hi:[1,0]
	v_pk_mul_f32 v[96:97], v[96:97], v[104:105] op_sel_hi:[1,0]
	v_pk_mul_f32 v[98:99], v[98:99], v[104:105] op_sel_hi:[1,0]
	v_pk_mul_f32 v[100:101], v[228:229], v[100:101]
	v_pk_mul_f32 v[102:103], v[230:231], v[102:103]
	v_cvt_pk_bf16_f32 v100, v100, v101
	s_nop 0
	v_cvt_pk_bf16_f32 v101, v102, v103
	v_pk_mul_f32 v[96:97], v[232:233], v[96:97]
	s_nop 0
	v_cvt_pk_bf16_f32 v102, v96, v97
	v_mad_u64_u32 v[96:97], s[0:1], v105, s33, v[140:141]
	v_mov_b32_e32 v97, v161
	v_lshl_add_u64 v[96:97], v[96:97], 1, s[62:63]
	v_pk_mul_f32 v[98:99], v[234:235], v[98:99]
	s_nop 0
	v_cvt_pk_bf16_f32 v103, v98, v99
	global_store_dwordx4 v[96:97], v[100:103], off
	v_or_b32_e32 v96, 32, v146
	s_nop 0
	v_lshl_add_u32 v103, v96, 5, s24
	v_add_u32_e32 v102, s25, v96
	ds_read_b128 v[96:99], v103
	s_waitcnt lgkmcnt(0)
	v_mov_b32_e32 v100, v97
	v_mov_b32_e32 v101, v98
	v_mov_b32_e32 v97, v99
	v_pk_add_f32 v[96:97], v[100:101], v[96:97]
	s_nop 0
	v_add_f32_e32 v96, v96, v97
	v_fmamk_f32 v96, v96, 0x3c000000, v199
	v_cmp_gt_f32_e32 vcc, s46, v96
	v_mul_f32_e32 v97, 0x4f800000, v96
	s_nop 0
	v_cndmask_b32_e32 v96, v96, v97, vcc
	v_sqrt_f32_e32 v97, v96
	s_nop 0
	v_add_u32_e32 v98, -1, v97
	v_fma_f32 v99, -v98, v97, v96
	v_cmp_ge_f32_e64 s[0:1], 0, v99
	v_add_u32_e32 v99, 1, v97
	s_nop 0
	v_cndmask_b32_e64 v98, v97, v98, s[0:1]
	v_fma_f32 v97, -v99, v97, v96
	v_cmp_lt_f32_e64 s[0:1], 0, v97
	s_nop 1
	v_cndmask_b32_e64 v97, v98, v99, s[0:1]
	v_mul_f32_e32 v98, 0x37800000, v97
	v_cndmask_b32_e32 v97, v97, v98, vcc
	v_cmp_class_f32_e32 vcc, v96, v201
	s_nop 1
	v_cndmask_b32_e32 v96, v97, v96, vcc
	v_div_scale_f32 v97, s[0:1], v96, v96, 1.0
	v_rcp_f32_e32 v98, v97
	s_nop 0
	v_fma_f32 v99, -v97, v98, 1.0
	v_fmac_f32_e32 v98, v99, v98
	v_div_scale_f32 v99, vcc, 1.0, v96, 1.0
	v_mul_f32_e32 v100, v99, v98
	v_fma_f32 v101, -v97, v100, v99
	v_fmac_f32_e32 v100, v101, v98
	v_fma_f32 v97, -v97, v100, v99
	v_div_fmas_f32 v97, v97, v98, v100
	v_div_fixup_f32 v96, v97, v96, 1.0
	v_add_u32_e32 v97, s26, v102
	v_pk_mul_f32 v[92:93], v[92:93], v[96:97] op_sel_hi:[1,0]
	v_pk_mul_f32 v[94:95], v[94:95], v[96:97] op_sel_hi:[1,0]
	v_pk_mul_f32 v[88:89], v[88:89], v[96:97] op_sel_hi:[1,0]
	v_pk_mul_f32 v[90:91], v[90:91], v[96:97] op_sel_hi:[1,0]
	v_pk_mul_f32 v[92:93], v[228:229], v[92:93]
	v_pk_mul_f32 v[94:95], v[230:231], v[94:95]
	v_cvt_pk_bf16_f32 v92, v92, v93
	s_nop 0
	v_cvt_pk_bf16_f32 v93, v94, v95
	v_pk_mul_f32 v[88:89], v[232:233], v[88:89]
	s_nop 0
	v_cvt_pk_bf16_f32 v94, v88, v89
	v_mad_u64_u32 v[88:89], s[0:1], v97, s33, v[140:141]
	v_mov_b32_e32 v89, v161
	v_pk_mul_f32 v[90:91], v[234:235], v[90:91]
	v_lshl_add_u64 v[88:89], v[88:89], 1, s[62:63]
	v_cvt_pk_bf16_f32 v95, v90, v91
	global_store_dwordx4 v[88:89], v[92:95], off
	ds_read_b128 v[88:91], v103 offset:16
	s_waitcnt lgkmcnt(0)
; #define PG8_LAS __attribute__((address_space(3)))
; __device__ __forceinline__ unsigned cvt_pk_bf16(float lo, float hi) { unsigned r; asm volatile("v_cvt_pk_bf16_f32 %0, %1, %2" : "=v"(r) : "v"(lo), "v"(hi)); return r; }
;     __device__ __forceinline__ void operator()(const f32x4 (&acc)[2][2][4][2], const Unit& u, int wr_, int wc_, int fr_, int fq_) const {
;     ...
;             for (int ai = 0; ai < 2; ++ai)
; #pragma unroll
;                 for (int m = 0; m < 4; ++m) { int rl = ai * HALF + wr * 64 + m * 16 + fr; asm volatile("" : "+v"(rl));
; #pragma unroll
;                     for (int bj = 0; bj < 2; ++bj) { const f32x4 pp = *(const PG8_LAS f32x4*)(P + (rl * 2 + bj) * 4);
;                         const float rr = 1.0f / sqrtf(((pp[0] + pp[1]) + (pp[2] + pp[3])) * (1.0f / 128.0f) + RMS_EPS_F);
;                         const int head = 2 * u.pn + bj;
;                         const unsigned qoff = (unsigned)(((b * 4 + head) * 8192 + s0 + rl) * 192 + wc * 32 + 8 * fq); u32x4 w;
; #pragma unroll
;                         for (int n = 0; n < 2; ++n) { const f32x4 g = *(const f32x4*)(gn_nope + wc * 32 + 8 * fq + 4 * n);
;                             const f32x4 v = acc[ai][bj][m][n] * rr * g; w[2 * n] = cvt_pk_bf16(v[0], v[1]); w[2 * n + 1] = cvt_pk_bf16(v[2], v[3]); }
;                         *(u32x4*)(Q + qoff) = w; }
	v_mov_b32_e32 v92, v89
	v_mov_b32_e32 v93, v90
	v_mov_b32_e32 v89, v91
	v_pk_add_f32 v[88:89], v[92:93], v[88:89]
	s_nop 0
	v_add_f32_e32 v88, v88, v89
	v_fmamk_f32 v88, v88, 0x3c000000, v199
	v_cmp_gt_f32_e32 vcc, s46, v88
	v_mul_f32_e32 v89, 0x4f800000, v88
	s_nop 0
	v_cndmask_b32_e32 v88, v88, v89, vcc
	v_sqrt_f32_e32 v89, v88
	s_nop 0
	v_add_u32_e32 v90, -1, v89
	v_fma_f32 v91, -v90, v89, v88
	v_cmp_ge_f32_e64 s[0:1], 0, v91
	v_add_u32_e32 v91, 1, v89
	s_nop 0
	v_cndmask_b32_e64 v90, v89, v90, s[0:1]
	v_fma_f32 v89, -v91, v89, v88
	v_cmp_lt_f32_e64 s[0:1], 0, v89
	s_nop 1
	v_cndmask_b32_e64 v89, v90, v91, s[0:1]
	v_mul_f32_e32 v90, 0x37800000, v89
	v_cndmask_b32_e32 v89, v89, v90, vcc
	v_cmp_class_f32_e32 vcc, v88, v201
	s_nop 1
	v_cndmask_b32_e32 v88, v89, v88, vcc
	v_div_scale_f32 v89, s[0:1], v88, v88, 1.0
	v_rcp_f32_e32 v90, v89
	s_nop 0
	v_fma_f32 v91, -v89, v90, 1.0
	v_fmac_f32_e32 v90, v91, v90
	v_div_scale_f32 v91, vcc, 1.0, v88, 1.0
	v_mul_f32_e32 v92, v91, v90
	v_fma_f32 v93, -v89, v92, v91
	v_fmac_f32_e32 v92, v93, v90
	v_fma_f32 v89, -v89, v92, v91
	v_div_fmas_f32 v89, v89, v90, v92
	v_div_fixup_f32 v88, v89, v88, 1.0
	v_add_u32_e32 v89, s27, v102
	v_pk_mul_f32 v[84:85], v[84:85], v[88:89] op_sel_hi:[1,0]
	v_pk_mul_f32 v[86:87], v[86:87], v[88:89] op_sel_hi:[1,0]
	v_pk_mul_f32 v[80:81], v[80:81], v[88:89] op_sel_hi:[1,0]
	v_pk_mul_f32 v[82:83], v[82:83], v[88:89] op_sel_hi:[1,0]
	v_pk_mul_f32 v[84:85], v[228:229], v[84:85]
	v_pk_mul_f32 v[86:87], v[230:231], v[86:87]
	v_cvt_pk_bf16_f32 v84, v84, v85
	s_nop 0
	v_cvt_pk_bf16_f32 v85, v86, v87
	v_pk_mul_f32 v[80:81], v[232:233], v[80:81]
	s_nop 0
	v_cvt_pk_bf16_f32 v86, v80, v81
	v_mad_u64_u32 v[80:81], s[0:1], v89, s33, v[140:141]
	v_mov_b32_e32 v81, v161
	v_lshl_add_u64 v[80:81], v[80:81], 1, s[62:63]
	v_pk_mul_f32 v[82:83], v[234:235], v[82:83]
	s_nop 0
	v_cvt_pk_bf16_f32 v87, v82, v83
	global_store_dwordx4 v[80:81], v[84:87], off
	v_or_b32_e32 v80, 48, v146
	s_nop 0
	v_lshl_add_u32 v87, v80, 5, s24
	v_add_u32_e32 v86, s25, v80
	ds_read_b128 v[80:83], v87
	s_waitcnt lgkmcnt(0)
	v_mov_b32_e32 v84, v81
	v_mov_b32_e32 v85, v82
	v_mov_b32_e32 v81, v83
	v_pk_add_f32 v[80:81], v[84:85], v[80:81]
	s_nop 0
	v_add_f32_e32 v80, v80, v81
	v_fmamk_f32 v80, v80, 0x3c000000, v199
	v_cmp_gt_f32_e32 vcc, s46, v80
	v_mul_f32_e32 v81, 0x4f800000, v80
	s_nop 0
	v_cndmask_b32_e32 v80, v80, v81, vcc
	v_sqrt_f32_e32 v81, v80
	s_nop 0
	v_add_u32_e32 v82, -1, v81
	v_fma_f32 v83, -v82, v81, v80
	v_cmp_ge_f32_e64 s[0:1], 0, v83
	v_add_u32_e32 v83, 1, v81
	s_nop 0
	v_cndmask_b32_e64 v82, v81, v82, s[0:1]
	v_fma_f32 v81, -v83, v81, v80
	v_cmp_lt_f32_e64 s[0:1], 0, v81
	s_nop 1
	v_cndmask_b32_e64 v81, v82, v83, s[0:1]
	v_mul_f32_e32 v82, 0x37800000, v81
	v_cndmask_b32_e32 v81, v81, v82, vcc
	v_cmp_class_f32_e32 vcc, v80, v201
	s_nop 1
	v_cndmask_b32_e32 v80, v81, v80, vcc
	v_div_scale_f32 v81, s[0:1], v80, v80, 1.0
	v_rcp_f32_e32 v82, v81
	s_nop 0
	v_fma_f32 v83, -v81, v82, 1.0
	v_fmac_f32_e32 v82, v83, v82
	v_div_scale_f32 v83, vcc, 1.0, v80, 1.0
	v_mul_f32_e32 v84, v83, v82
	v_fma_f32 v85, -v81, v84, v83
	v_fmac_f32_e32 v84, v85, v82
	v_fma_f32 v81, -v81, v84, v83
	v_div_fmas_f32 v81, v81, v82, v84
	v_div_fixup_f32 v80, v81, v80, 1.0
	v_add_u32_e32 v81, s26, v86
	v_pk_mul_f32 v[76:77], v[76:77], v[80:81] op_sel_hi:[1,0]
	v_pk_mul_f32 v[78:79], v[78:79], v[80:81] op_sel_hi:[1,0]
	v_pk_mul_f32 v[72:73], v[72:73], v[80:81] op_sel_hi:[1,0]
	v_pk_mul_f32 v[74:75], v[74:75], v[80:81] op_sel_hi:[1,0]
	v_pk_mul_f32 v[76:77], v[228:229], v[76:77]
	v_pk_mul_f32 v[78:79], v[230:231], v[78:79]
	v_cvt_pk_bf16_f32 v76, v76, v77
	s_nop 0
	v_cvt_pk_bf16_f32 v77, v78, v79
	v_pk_mul_f32 v[72:73], v[232:233], v[72:73]
	s_nop 0
	v_cvt_pk_bf16_f32 v78, v72, v73
	v_mad_u64_u32 v[72:73], s[0:1], v81, s33, v[140:141]
	v_mov_b32_e32 v73, v161
	v_pk_mul_f32 v[74:75], v[234:235], v[74:75]
	v_lshl_add_u64 v[72:73], v[72:73], 1, s[62:63]
	v_cvt_pk_bf16_f32 v79, v74, v75
	global_store_dwordx4 v[72:73], v[76:79], off
	ds_read_b128 v[72:75], v87 offset:16
	s_waitcnt lgkmcnt(0)
	v_mov_b32_e32 v76, v73
	v_mov_b32_e32 v77, v74
	v_mov_b32_e32 v73, v75
	v_pk_add_f32 v[72:73], v[76:77], v[72:73]
	s_nop 0
	v_add_f32_e32 v72, v72, v73
	v_fmamk_f32 v72, v72, 0x3c000000, v199
	v_cmp_gt_f32_e32 vcc, s46, v72
	v_mul_f32_e32 v73, 0x4f800000, v72
	s_nop 0
	v_cndmask_b32_e32 v72, v72, v73, vcc
	v_sqrt_f32_e32 v73, v72
	s_nop 0
	v_add_u32_e32 v74, -1, v73
	v_fma_f32 v75, -v74, v73, v72
	v_cmp_ge_f32_e64 s[0:1], 0, v75
	v_add_u32_e32 v75, 1, v73
	s_nop 0
	v_cndmask_b32_e64 v74, v73, v74, s[0:1]
	v_fma_f32 v73, -v75, v73, v72
	v_cmp_lt_f32_e64 s[0:1], 0, v73
	s_nop 1
	v_cndmask_b32_e64 v73, v74, v75, s[0:1]
	v_mul_f32_e32 v74, 0x37800000, v73
	v_cndmask_b32_e32 v73, v73, v74, vcc
	v_cmp_class_f32_e32 vcc, v72, v201
	s_nop 1
	v_cndmask_b32_e32 v72, v73, v72, vcc
	v_div_scale_f32 v73, s[0:1], v72, v72, 1.0
	v_rcp_f32_e32 v74, v73
	s_nop 0
	v_fma_f32 v75, -v73, v74, 1.0
	v_fmac_f32_e32 v74, v75, v74
	v_div_scale_f32 v75, vcc, 1.0, v72, 1.0
	v_mul_f32_e32 v76, v75, v74
	v_fma_f32 v77, -v73, v76, v75
	v_fmac_f32_e32 v76, v77, v74
	v_fma_f32 v73, -v73, v76, v75
	v_div_fmas_f32 v73, v73, v74, v76
	v_div_fixup_f32 v72, v73, v72, 1.0
	v_add_u32_e32 v73, s27, v86
	v_pk_mul_f32 v[68:69], v[68:69], v[72:73] op_sel_hi:[1,0]
	v_pk_mul_f32 v[70:71], v[70:71], v[72:73] op_sel_hi:[1,0]
	v_pk_mul_f32 v[64:65], v[64:65], v[72:73] op_sel_hi:[1,0]
	v_pk_mul_f32 v[66:67], v[66:67], v[72:73] op_sel_hi:[1,0]
	v_pk_mul_f32 v[68:69], v[228:229], v[68:69]
	v_pk_mul_f32 v[70:71], v[230:231], v[70:71]
	v_cvt_pk_bf16_f32 v68, v68, v69
	s_nop 0
	v_cvt_pk_bf16_f32 v69, v70, v71
	v_pk_mul_f32 v[64:65], v[232:233], v[64:65]
	s_nop 0
	v_cvt_pk_bf16_f32 v70, v64, v65
	v_mad_u64_u32 v[64:65], s[0:1], v73, s33, v[140:141]
	v_mov_b32_e32 v65, v161
	v_lshl_add_u64 v[64:65], v[64:65], 1, s[62:63]
	v_pk_mul_f32 v[66:67], v[234:235], v[66:67]
	s_nop 0
	v_cvt_pk_bf16_f32 v71, v66, v67
	global_store_dwordx4 v[64:65], v[68:71], off
	v_add_u32_e32 v64, 0x80, v146
	s_nop 0
	v_lshl_add_u32 v71, v64, 5, s24
	v_add_u32_e32 v70, s25, v64
	ds_read_b128 v[64:67], v71
	s_waitcnt lgkmcnt(0)
; #define PG8_LAS __attribute__((address_space(3)))
; __device__ __forceinline__ unsigned cvt_pk_bf16(float lo, float hi) { unsigned r; asm volatile("v_cvt_pk_bf16_f32 %0, %1, %2" : "=v"(r) : "v"(lo), "v"(hi)); return r; }
;     __device__ __forceinline__ void operator()(const f32x4 (&acc)[2][2][4][2], const Unit& u, int wr_, int wc_, int fr_, int fq_) const {
;     ...
;             for (int ai = 0; ai < 2; ++ai)
; #pragma unroll
;                 for (int m = 0; m < 4; ++m) { int rl = ai * HALF + wr * 64 + m * 16 + fr; asm volatile("" : "+v"(rl));
; #pragma unroll
;                     for (int bj = 0; bj < 2; ++bj) { const f32x4 pp = *(const PG8_LAS f32x4*)(P + (rl * 2 + bj) * 4);
;                         const float rr = 1.0f / sqrtf(((pp[0] + pp[1]) + (pp[2] + pp[3])) * (1.0f / 128.0f) + RMS_EPS_F);
;                         const int head = 2 * u.pn + bj;
;                         const unsigned qoff = (unsigned)(((b * 4 + head) * 8192 + s0 + rl) * 192 + wc * 32 + 8 * fq); u32x4 w;
; #pragma unroll
;                         for (int n = 0; n < 2; ++n) { const f32x4 g = *(const f32x4*)(gn_nope + wc * 32 + 8 * fq + 4 * n);
;                             const f32x4 v = acc[ai][bj][m][n] * rr * g; w[2 * n] = cvt_pk_bf16(v[0], v[1]); w[2 * n + 1] = cvt_pk_bf16(v[2], v[3]); }
;                         *(u32x4*)(Q + qoff) = w; }
	v_mov_b32_e32 v68, v65
	v_mov_b32_e32 v69, v66
	v_mov_b32_e32 v65, v67
	v_pk_add_f32 v[64:65], v[68:69], v[64:65]
	s_nop 0
	v_add_f32_e32 v64, v64, v65
	v_fmamk_f32 v64, v64, 0x3c000000, v199
	v_cmp_gt_f32_e32 vcc, s46, v64
	v_mul_f32_e32 v65, 0x4f800000, v64
	s_nop 0
	v_cndmask_b32_e32 v64, v64, v65, vcc
	v_sqrt_f32_e32 v65, v64
	s_nop 0
	v_add_u32_e32 v66, -1, v65
	v_fma_f32 v67, -v66, v65, v64
	v_cmp_ge_f32_e64 s[0:1], 0, v67
	v_add_u32_e32 v67, 1, v65
	s_nop 0
	v_cndmask_b32_e64 v66, v65, v66, s[0:1]
	v_fma_f32 v65, -v67, v65, v64
	v_cmp_lt_f32_e64 s[0:1], 0, v65
	s_nop 1
	v_cndmask_b32_e64 v65, v66, v67, s[0:1]
	v_mul_f32_e32 v66, 0x37800000, v65
	v_cndmask_b32_e32 v65, v65, v66, vcc
	v_cmp_class_f32_e32 vcc, v64, v201
	s_nop 1
	v_cndmask_b32_e32 v64, v65, v64, vcc
	v_div_scale_f32 v65, s[0:1], v64, v64, 1.0
	v_rcp_f32_e32 v66, v65
	s_nop 0
	v_fma_f32 v67, -v65, v66, 1.0
	v_fmac_f32_e32 v66, v67, v66
	v_div_scale_f32 v67, vcc, 1.0, v64, 1.0
	v_mul_f32_e32 v68, v67, v66
	v_fma_f32 v69, -v65, v68, v67
	v_fmac_f32_e32 v68, v69, v66
	v_fma_f32 v65, -v65, v68, v67
	v_div_fmas_f32 v65, v65, v66, v68
	v_div_fixup_f32 v64, v65, v64, 1.0
	v_add_u32_e32 v65, s26, v70
	v_pk_mul_f32 v[60:61], v[60:61], v[64:65] op_sel_hi:[1,0]
	v_pk_mul_f32 v[62:63], v[62:63], v[64:65] op_sel_hi:[1,0]
	v_pk_mul_f32 v[56:57], v[56:57], v[64:65] op_sel_hi:[1,0]
	v_pk_mul_f32 v[58:59], v[58:59], v[64:65] op_sel_hi:[1,0]
	v_pk_mul_f32 v[60:61], v[228:229], v[60:61]
	v_pk_mul_f32 v[62:63], v[230:231], v[62:63]
	v_cvt_pk_bf16_f32 v60, v60, v61
	s_nop 0
	v_cvt_pk_bf16_f32 v61, v62, v63
	v_pk_mul_f32 v[56:57], v[232:233], v[56:57]
	s_nop 0
	v_cvt_pk_bf16_f32 v62, v56, v57
	v_mad_u64_u32 v[56:57], s[0:1], v65, s33, v[140:141]
	v_mov_b32_e32 v57, v161
	v_pk_mul_f32 v[58:59], v[234:235], v[58:59]
	v_lshl_add_u64 v[56:57], v[56:57], 1, s[62:63]
	v_cvt_pk_bf16_f32 v63, v58, v59
	global_store_dwordx4 v[56:57], v[60:63], off
	ds_read_b128 v[56:59], v71 offset:16
	s_waitcnt lgkmcnt(0)
	v_mov_b32_e32 v60, v57
	v_mov_b32_e32 v61, v58
	v_mov_b32_e32 v57, v59
	v_pk_add_f32 v[56:57], v[60:61], v[56:57]
	s_nop 0
	v_add_f32_e32 v56, v56, v57
	v_fmamk_f32 v56, v56, 0x3c000000, v199
	v_cmp_gt_f32_e32 vcc, s46, v56
	v_mul_f32_e32 v57, 0x4f800000, v56
	s_nop 0
	v_cndmask_b32_e32 v56, v56, v57, vcc
	v_sqrt_f32_e32 v57, v56
	s_nop 0
	v_add_u32_e32 v58, -1, v57
	v_fma_f32 v59, -v58, v57, v56
	v_cmp_ge_f32_e64 s[0:1], 0, v59
	v_add_u32_e32 v59, 1, v57
	s_nop 0
	v_cndmask_b32_e64 v58, v57, v58, s[0:1]
	v_fma_f32 v57, -v59, v57, v56
	v_cmp_lt_f32_e64 s[0:1], 0, v57
	s_nop 1
	v_cndmask_b32_e64 v57, v58, v59, s[0:1]
	v_mul_f32_e32 v58, 0x37800000, v57
	v_cndmask_b32_e32 v57, v57, v58, vcc
	v_cmp_class_f32_e32 vcc, v56, v201
	s_nop 1
	v_cndmask_b32_e32 v56, v57, v56, vcc
	v_div_scale_f32 v57, s[0:1], v56, v56, 1.0
	v_rcp_f32_e32 v58, v57
	s_nop 0
	v_fma_f32 v59, -v57, v58, 1.0
	v_fmac_f32_e32 v58, v59, v58
	v_div_scale_f32 v59, vcc, 1.0, v56, 1.0
	v_mul_f32_e32 v60, v59, v58
	v_fma_f32 v61, -v57, v60, v59
	v_fmac_f32_e32 v60, v61, v58
	v_fma_f32 v57, -v57, v60, v59
	v_div_fmas_f32 v57, v57, v58, v60
	v_div_fixup_f32 v56, v57, v56, 1.0
	v_add_u32_e32 v57, s27, v70
	v_pk_mul_f32 v[52:53], v[52:53], v[56:57] op_sel_hi:[1,0]
	v_pk_mul_f32 v[54:55], v[54:55], v[56:57] op_sel_hi:[1,0]
	v_pk_mul_f32 v[48:49], v[48:49], v[56:57] op_sel_hi:[1,0]
	v_pk_mul_f32 v[50:51], v[50:51], v[56:57] op_sel_hi:[1,0]
	v_pk_mul_f32 v[52:53], v[228:229], v[52:53]
	v_pk_mul_f32 v[54:55], v[230:231], v[54:55]
	v_cvt_pk_bf16_f32 v52, v52, v53
	s_nop 0
	v_cvt_pk_bf16_f32 v53, v54, v55
	v_pk_mul_f32 v[48:49], v[232:233], v[48:49]
	s_nop 0
	v_cvt_pk_bf16_f32 v54, v48, v49
	v_mad_u64_u32 v[48:49], s[0:1], v57, s33, v[140:141]
	v_mov_b32_e32 v49, v161
	v_lshl_add_u64 v[48:49], v[48:49], 1, s[62:63]
	v_pk_mul_f32 v[50:51], v[234:235], v[50:51]
	s_nop 0
	v_cvt_pk_bf16_f32 v55, v50, v51
	global_store_dwordx4 v[48:49], v[52:55], off
	v_add_u32_e32 v48, 0x90, v146
	s_nop 0
	v_lshl_add_u32 v55, v48, 5, s24
	v_add_u32_e32 v54, s25, v48
	ds_read_b128 v[48:51], v55
	s_waitcnt lgkmcnt(0)
	v_mov_b32_e32 v52, v49
	v_mov_b32_e32 v53, v50
	v_mov_b32_e32 v49, v51
	v_pk_add_f32 v[48:49], v[52:53], v[48:49]
	s_nop 0
	v_add_f32_e32 v48, v48, v49
	v_fmamk_f32 v48, v48, 0x3c000000, v199
	v_cmp_gt_f32_e32 vcc, s46, v48
	v_mul_f32_e32 v49, 0x4f800000, v48
	s_nop 0
	v_cndmask_b32_e32 v48, v48, v49, vcc
	v_sqrt_f32_e32 v49, v48
	s_nop 0
	v_add_u32_e32 v50, -1, v49
	v_fma_f32 v51, -v50, v49, v48
	v_cmp_ge_f32_e64 s[0:1], 0, v51
	v_add_u32_e32 v51, 1, v49
	s_nop 0
	v_cndmask_b32_e64 v50, v49, v50, s[0:1]
	v_fma_f32 v49, -v51, v49, v48
	v_cmp_lt_f32_e64 s[0:1], 0, v49
	s_nop 1
	v_cndmask_b32_e64 v49, v50, v51, s[0:1]
	v_mul_f32_e32 v50, 0x37800000, v49
	v_cndmask_b32_e32 v49, v49, v50, vcc
	v_cmp_class_f32_e32 vcc, v48, v201
	s_nop 1
	v_cndmask_b32_e32 v48, v49, v48, vcc
	v_div_scale_f32 v49, s[0:1], v48, v48, 1.0
	v_rcp_f32_e32 v50, v49
	s_nop 0
	v_fma_f32 v51, -v49, v50, 1.0
	v_fmac_f32_e32 v50, v51, v50
	v_div_scale_f32 v51, vcc, 1.0, v48, 1.0
	v_mul_f32_e32 v52, v51, v50
	v_fma_f32 v53, -v49, v52, v51
	v_fmac_f32_e32 v52, v53, v50
	v_fma_f32 v49, -v49, v52, v51
	v_div_fmas_f32 v49, v49, v50, v52
	v_div_fixup_f32 v48, v49, v48, 1.0
	v_add_u32_e32 v49, s26, v54
	v_pk_mul_f32 v[44:45], v[44:45], v[48:49] op_sel_hi:[1,0]
	v_pk_mul_f32 v[46:47], v[46:47], v[48:49] op_sel_hi:[1,0]
	v_pk_mul_f32 v[40:41], v[40:41], v[48:49] op_sel_hi:[1,0]
	v_pk_mul_f32 v[42:43], v[42:43], v[48:49] op_sel_hi:[1,0]
	v_pk_mul_f32 v[44:45], v[228:229], v[44:45]
	v_pk_mul_f32 v[46:47], v[230:231], v[46:47]
	v_cvt_pk_bf16_f32 v44, v44, v45
	s_nop 0
	v_cvt_pk_bf16_f32 v45, v46, v47
	v_pk_mul_f32 v[40:41], v[232:233], v[40:41]
	s_nop 0
	v_cvt_pk_bf16_f32 v46, v40, v41
	v_mad_u64_u32 v[40:41], s[0:1], v49, s33, v[140:141]
	v_mov_b32_e32 v41, v161
	v_pk_mul_f32 v[42:43], v[234:235], v[42:43]
	v_lshl_add_u64 v[40:41], v[40:41], 1, s[62:63]
	v_cvt_pk_bf16_f32 v47, v42, v43
	global_store_dwordx4 v[40:41], v[44:47], off
	ds_read_b128 v[40:43], v55 offset:16
	s_waitcnt lgkmcnt(0)
; #define PG8_LAS __attribute__((address_space(3)))
; __device__ __forceinline__ unsigned cvt_pk_bf16(float lo, float hi) { unsigned r; asm volatile("v_cvt_pk_bf16_f32 %0, %1, %2" : "=v"(r) : "v"(lo), "v"(hi)); return r; }
;     __device__ __forceinline__ void operator()(const f32x4 (&acc)[2][2][4][2], const Unit& u, int wr_, int wc_, int fr_, int fq_) const {
;     ...
;             for (int ai = 0; ai < 2; ++ai)
; #pragma unroll
;                 for (int m = 0; m < 4; ++m) { int rl = ai * HALF + wr * 64 + m * 16 + fr; asm volatile("" : "+v"(rl));
; #pragma unroll
;                     for (int bj = 0; bj < 2; ++bj) { const f32x4 pp = *(const PG8_LAS f32x4*)(P + (rl * 2 + bj) * 4);
;                         const float rr = 1.0f / sqrtf(((pp[0] + pp[1]) + (pp[2] + pp[3])) * (1.0f / 128.0f) + RMS_EPS_F);
;                         const int head = 2 * u.pn + bj;
;                         const unsigned qoff = (unsigned)(((b * 4 + head) * 8192 + s0 + rl) * 192 + wc * 32 + 8 * fq); u32x4 w;
; #pragma unroll
;                         for (int n = 0; n < 2; ++n) { const f32x4 g = *(const f32x4*)(gn_nope + wc * 32 + 8 * fq + 4 * n);
;                             const f32x4 v = acc[ai][bj][m][n] * rr * g; w[2 * n] = cvt_pk_bf16(v[0], v[1]); w[2 * n + 1] = cvt_pk_bf16(v[2], v[3]); }
;                         *(u32x4*)(Q + qoff) = w; }
	v_mov_b32_e32 v44, v41
	v_mov_b32_e32 v45, v42
	v_mov_b32_e32 v41, v43
	v_pk_add_f32 v[40:41], v[44:45], v[40:41]
	s_nop 0
	v_add_f32_e32 v40, v40, v41
	v_fmamk_f32 v40, v40, 0x3c000000, v199
	v_cmp_gt_f32_e32 vcc, s46, v40
	v_mul_f32_e32 v41, 0x4f800000, v40
	s_nop 0
	v_cndmask_b32_e32 v40, v40, v41, vcc
	v_sqrt_f32_e32 v41, v40
	s_nop 0
	v_add_u32_e32 v42, -1, v41
	v_fma_f32 v43, -v42, v41, v40
	v_cmp_ge_f32_e64 s[0:1], 0, v43
	v_add_u32_e32 v43, 1, v41
	s_nop 0
	v_cndmask_b32_e64 v42, v41, v42, s[0:1]
	v_fma_f32 v41, -v43, v41, v40
	v_cmp_lt_f32_e64 s[0:1], 0, v41
	s_nop 1
	v_cndmask_b32_e64 v41, v42, v43, s[0:1]
	v_mul_f32_e32 v42, 0x37800000, v41
	v_cndmask_b32_e32 v41, v41, v42, vcc
	v_cmp_class_f32_e32 vcc, v40, v201
	s_nop 1
	v_cndmask_b32_e32 v40, v41, v40, vcc
	v_div_scale_f32 v41, s[0:1], v40, v40, 1.0
	v_rcp_f32_e32 v42, v41
	s_nop 0
	v_fma_f32 v43, -v41, v42, 1.0
	v_fmac_f32_e32 v42, v43, v42
	v_div_scale_f32 v43, vcc, 1.0, v40, 1.0
	v_mul_f32_e32 v44, v43, v42
	v_fma_f32 v45, -v41, v44, v43
	v_fmac_f32_e32 v44, v45, v42
	v_fma_f32 v41, -v41, v44, v43
	v_div_fmas_f32 v41, v41, v42, v44
	v_div_fixup_f32 v40, v41, v40, 1.0
	v_add_u32_e32 v41, s27, v54
	v_pk_mul_f32 v[36:37], v[36:37], v[40:41] op_sel_hi:[1,0]
	v_pk_mul_f32 v[38:39], v[38:39], v[40:41] op_sel_hi:[1,0]
	v_pk_mul_f32 v[32:33], v[32:33], v[40:41] op_sel_hi:[1,0]
	v_pk_mul_f32 v[34:35], v[34:35], v[40:41] op_sel_hi:[1,0]
	v_pk_mul_f32 v[36:37], v[228:229], v[36:37]
	v_pk_mul_f32 v[38:39], v[230:231], v[38:39]
	v_cvt_pk_bf16_f32 v36, v36, v37
	s_nop 0
	v_cvt_pk_bf16_f32 v37, v38, v39
	v_pk_mul_f32 v[32:33], v[232:233], v[32:33]
	s_nop 0
	v_cvt_pk_bf16_f32 v38, v32, v33
	v_mad_u64_u32 v[32:33], s[0:1], v41, s33, v[140:141]
	v_mov_b32_e32 v33, v161
	v_lshl_add_u64 v[32:33], v[32:33], 1, s[62:63]
	v_pk_mul_f32 v[34:35], v[234:235], v[34:35]
	s_nop 0
	v_cvt_pk_bf16_f32 v39, v34, v35
	global_store_dwordx4 v[32:33], v[36:39], off
	v_add_u32_e32 v32, 0xa0, v146
	s_nop 0
	v_lshl_add_u32 v39, v32, 5, s24
	v_add_u32_e32 v38, s25, v32
	ds_read_b128 v[32:35], v39
	s_waitcnt lgkmcnt(0)
	v_mov_b32_e32 v36, v33
	v_mov_b32_e32 v37, v34
	v_mov_b32_e32 v33, v35
	v_pk_add_f32 v[32:33], v[36:37], v[32:33]
	s_nop 0
	v_add_f32_e32 v32, v32, v33
	v_fmamk_f32 v32, v32, 0x3c000000, v199
	v_cmp_gt_f32_e32 vcc, s46, v32
	v_mul_f32_e32 v33, 0x4f800000, v32
	s_nop 0
	v_cndmask_b32_e32 v32, v32, v33, vcc
	v_sqrt_f32_e32 v33, v32
	s_nop 0
	v_add_u32_e32 v34, -1, v33
	v_fma_f32 v35, -v34, v33, v32
	v_cmp_ge_f32_e64 s[0:1], 0, v35
	v_add_u32_e32 v35, 1, v33
	s_nop 0
	v_cndmask_b32_e64 v34, v33, v34, s[0:1]
	v_fma_f32 v33, -v35, v33, v32
	v_cmp_lt_f32_e64 s[0:1], 0, v33
	s_nop 1
	v_cndmask_b32_e64 v33, v34, v35, s[0:1]
	v_mul_f32_e32 v34, 0x37800000, v33
	v_cndmask_b32_e32 v33, v33, v34, vcc
	v_cmp_class_f32_e32 vcc, v32, v201
	s_nop 1
	v_cndmask_b32_e32 v32, v33, v32, vcc
	v_div_scale_f32 v33, s[0:1], v32, v32, 1.0
	v_rcp_f32_e32 v34, v33
	s_nop 0
	v_fma_f32 v35, -v33, v34, 1.0
	v_fmac_f32_e32 v34, v35, v34
	v_div_scale_f32 v35, vcc, 1.0, v32, 1.0
	v_mul_f32_e32 v36, v35, v34
	v_fma_f32 v37, -v33, v36, v35
	v_fmac_f32_e32 v36, v37, v34
	v_fma_f32 v33, -v33, v36, v35
	v_div_fmas_f32 v33, v33, v34, v36
	v_div_fixup_f32 v32, v33, v32, 1.0
	v_add_u32_e32 v33, s26, v38
	v_pk_mul_f32 v[28:29], v[28:29], v[32:33] op_sel_hi:[1,0]
	v_pk_mul_f32 v[30:31], v[30:31], v[32:33] op_sel_hi:[1,0]
	v_pk_mul_f32 v[24:25], v[24:25], v[32:33] op_sel_hi:[1,0]
	v_pk_mul_f32 v[26:27], v[26:27], v[32:33] op_sel_hi:[1,0]
	v_pk_mul_f32 v[28:29], v[228:229], v[28:29]
	v_pk_mul_f32 v[30:31], v[230:231], v[30:31]
	v_cvt_pk_bf16_f32 v28, v28, v29
	s_nop 0
	v_cvt_pk_bf16_f32 v29, v30, v31
	v_pk_mul_f32 v[24:25], v[232:233], v[24:25]
	s_nop 0
	v_cvt_pk_bf16_f32 v30, v24, v25
	v_mad_u64_u32 v[24:25], s[0:1], v33, s33, v[140:141]
	v_mov_b32_e32 v25, v161
	v_pk_mul_f32 v[26:27], v[234:235], v[26:27]
	v_lshl_add_u64 v[24:25], v[24:25], 1, s[62:63]
	v_cvt_pk_bf16_f32 v31, v26, v27
	global_store_dwordx4 v[24:25], v[28:31], off
	ds_read_b128 v[24:27], v39 offset:16
	s_waitcnt lgkmcnt(0)
; #define PG8_LAS __attribute__((address_space(3)))
; __device__ __forceinline__ unsigned cvt_pk_bf16(float lo, float hi) { unsigned r; asm volatile("v_cvt_pk_bf16_f32 %0, %1, %2" : "=v"(r) : "v"(lo), "v"(hi)); return r; }
; #define PG8_BAR __builtin_amdgcn_s_barrier()
; template <class Epi, class Sched, bool ALIGN_EPI = false, bool SP2 = false>
; __device__ __forceinline__ void gemm_phase(PG8_LAS unsigned char* lds, const Gemm g, const Sched& S, const Epi& E) {
;     ...
;         if constexpr (!Epi::AFTER_DRAIN) { E(acc, cur, wr, wc, fr, fq); S.done(cur); }
;         if (!has_next) break;
; #pragma unroll
;         for (int a = 0; a < 2; ++a)
; #pragma unroll
;             for (int b = 0; b < 2; ++b)
; #pragma unroll
;                 for (int m = 0; m < 4; ++m)
; #pragma unroll
;                     for (int n = 0; n < 2; ++n) acc[a][b][m][n] = (f32x4){0.f, 0.f, 0.f, 0.f};
;         cur = nxt; cA = nA; cB = nB; ++ui;
;         if constexpr (ALIGN_EPI) { if (wr == 1) PG8_BAR; }
;     __device__ __forceinline__ void operator()(const f32x4 (&acc)[2][2][4][2], const Unit& u, int wr_, int wc_, int fr_, int fq_) const {
;     ...
;             for (int ai = 0; ai < 2; ++ai)
; #pragma unroll
;                 for (int m = 0; m < 4; ++m) { int rl = ai * HALF + wr * 64 + m * 16 + fr; asm volatile("" : "+v"(rl));
; #pragma unroll
;                     for (int bj = 0; bj < 2; ++bj) { const f32x4 pp = *(const PG8_LAS f32x4*)(P + (rl * 2 + bj) * 4);
;                         const float rr = 1.0f / sqrtf(((pp[0] + pp[1]) + (pp[2] + pp[3])) * (1.0f / 128.0f) + RMS_EPS_F);
;                         const int head = 2 * u.pn + bj;
;                         const unsigned qoff = (unsigned)(((b * 4 + head) * 8192 + s0 + rl) * 192 + wc * 32 + 8 * fq); u32x4 w;
; #pragma unroll
;                         for (int n = 0; n < 2; ++n) { const f32x4 g = *(const f32x4*)(gn_nope + wc * 32 + 8 * fq + 4 * n);
;                             const f32x4 v = acc[ai][bj][m][n] * rr * g; w[2 * n] = cvt_pk_bf16(v[0], v[1]); w[2 * n + 1] = cvt_pk_bf16(v[2], v[3]); }
;                         *(u32x4*)(Q + qoff) = w; }
	v_mov_b32_e32 v28, v25
	v_mov_b32_e32 v29, v26
	v_mov_b32_e32 v25, v27
	v_pk_add_f32 v[24:25], v[28:29], v[24:25]
	s_nop 0
	v_add_f32_e32 v24, v24, v25
	v_fmamk_f32 v24, v24, 0x3c000000, v199
	v_cmp_gt_f32_e32 vcc, s46, v24
	v_mul_f32_e32 v25, 0x4f800000, v24
	s_nop 0
	v_cndmask_b32_e32 v24, v24, v25, vcc
	v_sqrt_f32_e32 v25, v24
	s_nop 0
	v_add_u32_e32 v26, -1, v25
	v_fma_f32 v27, -v26, v25, v24
	v_cmp_ge_f32_e64 s[0:1], 0, v27
	v_add_u32_e32 v27, 1, v25
	s_nop 0
	v_cndmask_b32_e64 v26, v25, v26, s[0:1]
	v_fma_f32 v25, -v27, v25, v24
	v_cmp_lt_f32_e64 s[0:1], 0, v25
	s_nop 1
	v_cndmask_b32_e64 v25, v26, v27, s[0:1]
	v_mul_f32_e32 v26, 0x37800000, v25
	v_cndmask_b32_e32 v25, v25, v26, vcc
	v_cmp_class_f32_e32 vcc, v24, v201
	s_nop 1
	v_cndmask_b32_e32 v24, v25, v24, vcc
	v_div_scale_f32 v25, s[0:1], v24, v24, 1.0
	v_rcp_f32_e32 v26, v25
	s_nop 0
	v_fma_f32 v27, -v25, v26, 1.0
	v_fmac_f32_e32 v26, v27, v26
	v_div_scale_f32 v27, vcc, 1.0, v24, 1.0
	v_mul_f32_e32 v28, v27, v26
	v_fma_f32 v29, -v25, v28, v27
	v_fmac_f32_e32 v28, v29, v26
	v_fma_f32 v25, -v25, v28, v27
	v_div_fmas_f32 v25, v25, v26, v28
	v_div_fixup_f32 v24, v25, v24, 1.0
	v_add_u32_e32 v25, s27, v38
	v_pk_mul_f32 v[20:21], v[20:21], v[24:25] op_sel_hi:[1,0]
	v_pk_mul_f32 v[22:23], v[22:23], v[24:25] op_sel_hi:[1,0]
	v_pk_mul_f32 v[16:17], v[16:17], v[24:25] op_sel_hi:[1,0]
	v_pk_mul_f32 v[18:19], v[18:19], v[24:25] op_sel_hi:[1,0]
	v_pk_mul_f32 v[20:21], v[228:229], v[20:21]
	v_pk_mul_f32 v[22:23], v[230:231], v[22:23]
	v_cvt_pk_bf16_f32 v20, v20, v21
	s_nop 0
	v_cvt_pk_bf16_f32 v21, v22, v23
	v_pk_mul_f32 v[16:17], v[232:233], v[16:17]
	s_nop 0
	v_cvt_pk_bf16_f32 v22, v16, v17
	v_mad_u64_u32 v[16:17], s[0:1], v25, s33, v[140:141]
	v_mov_b32_e32 v17, v161
	v_lshl_add_u64 v[16:17], v[16:17], 1, s[62:63]
	v_pk_mul_f32 v[18:19], v[234:235], v[18:19]
	s_nop 0
	v_cvt_pk_bf16_f32 v23, v18, v19
	global_store_dwordx4 v[16:17], v[20:23], off
	v_add_u32_e32 v16, 0xb0, v146
	s_nop 0
	v_lshl_add_u32 v23, v16, 5, s24
	v_add_u32_e32 v22, s25, v16
	ds_read_b128 v[16:19], v23
	s_waitcnt lgkmcnt(0)
	v_mov_b32_e32 v20, v17
	v_mov_b32_e32 v21, v18
	v_mov_b32_e32 v17, v19
	v_pk_add_f32 v[16:17], v[20:21], v[16:17]
	s_nop 0
	v_add_f32_e32 v16, v16, v17
	v_fmamk_f32 v16, v16, 0x3c000000, v199
	v_cmp_gt_f32_e32 vcc, s46, v16
	v_mul_f32_e32 v17, 0x4f800000, v16
	s_nop 0
	v_cndmask_b32_e32 v16, v16, v17, vcc
	v_sqrt_f32_e32 v17, v16
	s_nop 0
	v_add_u32_e32 v18, -1, v17
	v_fma_f32 v19, -v18, v17, v16
	v_cmp_ge_f32_e64 s[0:1], 0, v19
	v_add_u32_e32 v19, 1, v17
	s_nop 0
	v_cndmask_b32_e64 v18, v17, v18, s[0:1]
	v_fma_f32 v17, -v19, v17, v16
	v_cmp_lt_f32_e64 s[0:1], 0, v17
	s_nop 1
	v_cndmask_b32_e64 v17, v18, v19, s[0:1]
	v_mul_f32_e32 v18, 0x37800000, v17
	v_cndmask_b32_e32 v17, v17, v18, vcc
	v_cmp_class_f32_e32 vcc, v16, v201
	s_nop 1
	v_cndmask_b32_e32 v16, v17, v16, vcc
	v_div_scale_f32 v17, s[0:1], v16, v16, 1.0
	v_rcp_f32_e32 v18, v17
	s_nop 0
	v_fma_f32 v19, -v17, v18, 1.0
	v_fmac_f32_e32 v18, v19, v18
	v_div_scale_f32 v19, vcc, 1.0, v16, 1.0
	v_mul_f32_e32 v20, v19, v18
	v_fma_f32 v21, -v17, v20, v19
	v_fmac_f32_e32 v20, v21, v18
	v_fma_f32 v17, -v17, v20, v19
	v_div_fmas_f32 v17, v17, v18, v20
	v_div_fixup_f32 v16, v17, v16, 1.0
	v_add_u32_e32 v17, s26, v22
	v_pk_mul_f32 v[12:13], v[12:13], v[16:17] op_sel_hi:[1,0]
	v_pk_mul_f32 v[14:15], v[14:15], v[16:17] op_sel_hi:[1,0]
	v_pk_mul_f32 v[8:9], v[8:9], v[16:17] op_sel_hi:[1,0]
	v_pk_mul_f32 v[10:11], v[10:11], v[16:17] op_sel_hi:[1,0]
	v_pk_mul_f32 v[12:13], v[228:229], v[12:13]
	v_pk_mul_f32 v[14:15], v[230:231], v[14:15]
	v_cvt_pk_bf16_f32 v12, v12, v13
	s_nop 0
	v_cvt_pk_bf16_f32 v13, v14, v15
	v_pk_mul_f32 v[8:9], v[232:233], v[8:9]
	s_nop 0
	v_cvt_pk_bf16_f32 v14, v8, v9
	v_mad_u64_u32 v[8:9], s[0:1], v17, s33, v[140:141]
	v_mov_b32_e32 v9, v161
	v_pk_mul_f32 v[10:11], v[234:235], v[10:11]
	v_lshl_add_u64 v[8:9], v[8:9], 1, s[62:63]
	v_cvt_pk_bf16_f32 v15, v10, v11
	global_store_dwordx4 v[8:9], v[12:15], off
	ds_read_b128 v[8:11], v23 offset:16
	s_waitcnt lgkmcnt(0)
	v_mov_b32_e32 v12, v9
	v_mov_b32_e32 v13, v10
	v_mov_b32_e32 v9, v11
	v_pk_add_f32 v[8:9], v[12:13], v[8:9]
	s_nop 0
	v_add_f32_e32 v8, v8, v9
	v_fmamk_f32 v8, v8, 0x3c000000, v199
	v_cmp_gt_f32_e32 vcc, s46, v8
	v_mul_f32_e32 v9, 0x4f800000, v8
	s_nop 0
	v_cndmask_b32_e32 v8, v8, v9, vcc
	v_sqrt_f32_e32 v9, v8
	s_nop 0
	v_add_u32_e32 v10, -1, v9
	v_fma_f32 v11, -v10, v9, v8
	v_cmp_ge_f32_e64 s[0:1], 0, v11
	v_add_u32_e32 v11, 1, v9
	s_nop 0
	v_cndmask_b32_e64 v10, v9, v10, s[0:1]
	v_fma_f32 v9, -v11, v9, v8
	v_cmp_lt_f32_e64 s[0:1], 0, v9
	s_nop 1
	v_cndmask_b32_e64 v9, v10, v11, s[0:1]
	v_mul_f32_e32 v10, 0x37800000, v9
	v_cndmask_b32_e32 v9, v9, v10, vcc
	v_cmp_class_f32_e32 vcc, v8, v201
	s_nop 1
	v_cndmask_b32_e32 v8, v9, v8, vcc
	v_div_scale_f32 v9, s[0:1], v8, v8, 1.0
	v_rcp_f32_e32 v10, v9
	s_nop 0
	v_fma_f32 v11, -v9, v10, 1.0
	v_fmac_f32_e32 v10, v11, v10
	v_div_scale_f32 v11, vcc, 1.0, v8, 1.0
	v_mul_f32_e32 v12, v11, v10
	v_fma_f32 v13, -v9, v12, v11
	v_fmac_f32_e32 v12, v13, v10
	v_fma_f32 v9, -v9, v12, v11
	v_div_fmas_f32 v9, v9, v10, v12
	v_div_fixup_f32 v8, v9, v8, 1.0
	v_add_u32_e32 v9, s27, v22
	v_pk_mul_f32 v[4:5], v[4:5], v[8:9] op_sel_hi:[1,0]
	v_pk_mul_f32 v[6:7], v[6:7], v[8:9] op_sel_hi:[1,0]
	v_pk_mul_f32 v[0:1], v[0:1], v[8:9] op_sel_hi:[1,0]
	v_pk_mul_f32 v[2:3], v[2:3], v[8:9] op_sel_hi:[1,0]
	s_and_b64 vcc, exec, s[2:3]
	v_pk_mul_f32 v[4:5], v[228:229], v[4:5]
	v_pk_mul_f32 v[6:7], v[230:231], v[6:7]
	v_cvt_pk_bf16_f32 v4, v4, v5
	s_nop 0
	v_cvt_pk_bf16_f32 v5, v6, v7
	v_pk_mul_f32 v[0:1], v[232:233], v[0:1]
	s_nop 0
	v_cvt_pk_bf16_f32 v6, v0, v1
	v_mad_u64_u32 v[0:1], s[0:1], v9, s33, v[140:141]
	v_mov_b32_e32 v1, v161
	v_lshl_add_u64 v[0:1], v[0:1], 1, s[62:63]
	v_pk_mul_f32 v[2:3], v[234:235], v[2:3]
	s_mov_b64 s[0:1], -1
	v_cvt_pk_bf16_f32 v7, v2, v3
	global_store_dwordx4 v[0:1], v[4:7], off
	s_cbranch_vccnz .LBB0_360
	s_andn2_b64 vcc, exec, s[12:13]
	s_cbranch_vccnz .LBB0_359
	s_barrier
	s_branch .LBB0_359

; #define PG8_LAS __attribute__((address_space(3)))
; __device__ __forceinline__ unsigned cvt_pk_bf16(float lo, float hi) { unsigned r; asm volatile("v_cvt_pk_bf16_f32 %0, %1, %2" : "=v"(r) : "v"(lo), "v"(hi)); return r; }
;     __device__ __forceinline__ void operator()(const f32x4 (&acc)[2][2][4][2], const Unit& u, int wr_, int wc_, int fr_, int fq_) const {
;     ...
;         asm volatile("s_waitcnt lgkmcnt(0)" ::: "memory"); __builtin_amdgcn_s_barrier(); asm volatile("" ::: "memory");
; #pragma unroll
;         for (int ai = 0; ai < 2; ++ai)
; #pragma unroll
;             for (int m = 0; m < 4; ++m) { int rl = ai * HALF + wr * 64 + m * 16 + fr; asm volatile("" : "+v"(rl));
;                 const f32x4 pp = *(const PG8_LAS f32x4*)(P + rl * 4);
;                 const float rr = 1.0f / sqrtf(((pp[0] + pp[1]) + (pp[2] + pp[3])) * (1.0f / 128.0f) + RMS_EPS_F);
;                 const size_t tok = (size_t)(b * 4 + u.pn) * 8192 + s0 + rl;
;                 bf16_t* krow = Kb + tok * 192; bf16_t* vrow = Vb + tok * 128;
;                 u32x4 w1, w2;
; #pragma unroll
;                 for (int n = 0; n < 2; ++n) { const f32x4 g = *(const f32x4*)(gn_k + wc * 32 + 8 * fq + 4 * n);
;                     const f32x4 kx = acc[ai][0][m][n] * rr * g, vx = acc[ai][1][m][n];
;                     w1[2 * n] = cvt_pk_bf16(kx[0], kx[1]); w1[2 * n + 1] = cvt_pk_bf16(kx[2], kx[3]); w2[2 * n] = cvt_pk_bf16(vx[0], vx[1]); w2[2 * n + 1] = cvt_pk_bf16(vx[2], vx[3]); }
;                 *(u32x4*)(krow + wc * 32 + 8 * fq) = w1; *(u32x4*)(vrow + wc * 32 + 8 * fq) = w2;
;                 asm volatile("" ::: "memory"); }
.LBB0_473:
	s_or_b64 exec, exec, s[6:7]
	v_lshl_or_b32 v149, v141, 6, v140
	v_mov_b32_e32 v144, v149
	s_waitcnt lgkmcnt(0)
	s_barrier
	s_lshl_b32 s6, s43, 8
	v_lshl_add_u32 v140, v144, 4, s24
	s_waitcnt lgkmcnt(0)
	ds_read_b128 v[140:143], v140
	s_and_b32 s25, s6, 0x1f00
	s_ashr_i32 s6, s43, 3
	s_and_b32 s6, s6, -4
	s_add_i32 s6, s6, s33
	s_waitcnt lgkmcnt(0)
	v_mov_b32_e32 v152, v141
	v_mov_b32_e32 v153, v142
	v_mov_b32_e32 v141, v143
	s_ashr_i32 s7, s6, 31
	v_pk_add_f32 v[140:141], v[152:153], v[140:141]
	s_lshl_b64 s[22:23], s[6:7], 13
	v_add_f32_e32 v140, v140, v141
	s_or_b32 s22, s22, s25
	v_fmamk_f32 v140, v140, 0x3c000000, v199
	s_mov_b32 s25, 0xf800000
	v_cmp_gt_f32_e32 vcc, s25, v140
	v_mul_f32_e32 v141, 0x4f800000, v140
	v_lshlrev_b32_e32 v160, 7, v151
	v_cndmask_b32_e32 v140, v140, v141, vcc
	v_sqrt_f32_e32 v141, v140
	s_nop 0
	v_add_u32_e32 v142, -1, v141
	v_fma_f32 v143, -v142, v141, v140
	v_cmp_ge_f32_e64 s[6:7], 0, v143
	v_add_u32_e32 v143, 1, v141
	s_nop 0
	v_cndmask_b32_e64 v142, v141, v142, s[6:7]
	v_fma_f32 v141, -v143, v141, v140
	v_cmp_lt_f32_e64 s[6:7], 0, v141
	s_nop 1
	v_cndmask_b32_e64 v141, v142, v143, s[6:7]
	v_mul_f32_e32 v142, 0x37800000, v141
	v_cndmask_b32_e32 v141, v141, v142, vcc
	v_cmp_class_f32_e32 vcc, v140, v201
	s_nop 1
	v_cndmask_b32_e32 v140, v141, v140, vcc
	v_div_scale_f32 v141, s[6:7], v140, v140, 1.0
	v_rcp_f32_e32 v142, v141
	s_nop 0
	v_fma_f32 v143, -v141, v142, 1.0
	v_fmac_f32_e32 v142, v143, v142
	v_div_scale_f32 v143, vcc, 1.0, v140, 1.0
	v_mul_f32_e32 v145, v143, v142
	v_fma_f32 v146, -v141, v145, v143
	v_fmac_f32_e32 v145, v146, v142
	v_fma_f32 v141, -v141, v145, v143
	v_div_fmas_f32 v141, v141, v142, v145
	v_div_fixup_f32 v146, v141, v140, 1.0
	v_lshl_add_u64 v[140:141], s[12:13], 0, v[160:161]
	v_lshlrev_b32_e32 v160, 5, v150
	v_lshl_add_u64 v[140:141], v[140:141], 0, v[160:161]
	global_load_dwordx4 v[228:231], v[140:141], off
	v_pk_mul_f32 v[124:125], v[124:125], v[146:147] op_sel_hi:[1,0]
	v_pk_mul_f32 v[126:127], v[126:127], v[146:147] op_sel_hi:[1,0]
	v_ashrrev_i32_e32 v145, 31, v144
	v_pk_mul_f32 v[116:117], v[116:117], v[146:147] op_sel_hi:[1,0]
	v_pk_mul_f32 v[118:119], v[118:119], v[146:147] op_sel_hi:[1,0]
	v_lshl_add_u64 v[142:143], s[22:23], 0, v[144:145]
	v_lshlrev_b64 v[144:145], 8, v[142:143]
	v_lshlrev_b32_e32 v160, 6, v151
	s_waitcnt vmcnt(0)
	v_pk_mul_f32 v[124:125], v[228:229], v[124:125]
	v_pk_mul_f32 v[126:127], v[230:231], v[126:127]
	v_cvt_pk_bf16_f32 v124, v124, v125
	s_nop 0
	v_cvt_pk_bf16_f32 v125, v126, v127
	v_cvt_pk_bf16_f32 v120, v120, v121
	v_cvt_pk_bf16_f32 v121, v122, v123
	global_load_dwordx4 v[232:235], v[140:141], off offset:16
	s_waitcnt vmcnt(0)
	v_pk_mul_f32 v[118:119], v[234:235], v[118:119]
	v_pk_mul_f32 v[116:117], v[232:233], v[116:117]
	s_nop 0
	v_cvt_pk_bf16_f32 v126, v116, v117
	v_cvt_pk_bf16_f32 v127, v118, v119
	v_cvt_pk_bf16_f32 v122, v112, v113
	v_mov_b64_e32 v[112:113], s[64:65]
	v_cvt_pk_bf16_f32 v123, v114, v115
	v_mad_u64_u32 v[114:115], s[6:7], v142, s67, v[112:113]
	v_mad_i32_i24 v115, v143, s67, v115
	v_lshl_add_u64 v[116:117], s[68:69], 0, v[144:145]
	v_lshl_add_u64 v[118:119], v[114:115], 0, v[160:161]
	v_lshlrev_b32_e32 v114, 4, v150
	v_mov_b32_e32 v115, v161
	v_lshl_add_u64 v[116:117], v[116:117], 0, v[160:161]
	v_lshl_add_u64 v[118:119], v[118:119], 0, v[114:115]
	v_lshl_add_u64 v[116:117], v[116:117], 0, v[114:115]
	global_store_dwordx4 v[118:119], v[124:127], off
	global_store_dwordx4 v[116:117], v[120:123], off
	s_nop 1
	v_or_b32_e32 v122, 16, v149
	s_nop 0
	v_lshl_add_u32 v116, v122, 4, s24
	ds_read_b128 v[116:119], v116
	v_ashrrev_i32_e32 v123, 31, v122
	s_waitcnt lgkmcnt(0)
	v_mov_b32_e32 v120, v117
	v_mov_b32_e32 v121, v118
	v_mov_b32_e32 v117, v119
	v_pk_add_f32 v[116:117], v[120:121], v[116:117]
	s_nop 0
	v_add_f32_e32 v116, v116, v117
	v_fmamk_f32 v116, v116, 0x3c000000, v199
	v_cmp_gt_f32_e32 vcc, s25, v116
	v_mul_f32_e32 v117, 0x4f800000, v116
	s_nop 0
	v_cndmask_b32_e32 v116, v116, v117, vcc
	v_sqrt_f32_e32 v117, v116
	s_nop 0
	v_add_u32_e32 v118, -1, v117
	v_fma_f32 v119, -v118, v117, v116
	v_cmp_ge_f32_e64 s[6:7], 0, v119
	v_add_u32_e32 v119, 1, v117
	s_nop 0
	v_cndmask_b32_e64 v118, v117, v118, s[6:7]
	v_fma_f32 v117, -v119, v117, v116
	v_cmp_lt_f32_e64 s[6:7], 0, v117
	s_nop 1
	v_cndmask_b32_e64 v117, v118, v119, s[6:7]
	v_mul_f32_e32 v118, 0x37800000, v117
	v_cndmask_b32_e32 v117, v117, v118, vcc
	v_cmp_class_f32_e32 vcc, v116, v201
	s_nop 1
	v_cndmask_b32_e32 v116, v117, v116, vcc
	v_div_scale_f32 v117, s[6:7], v116, v116, 1.0
	v_rcp_f32_e32 v118, v117
	s_nop 0
	v_fma_f32 v119, -v117, v118, 1.0
	v_fmac_f32_e32 v118, v119, v118
	v_div_scale_f32 v119, vcc, 1.0, v116, 1.0
	v_mul_f32_e32 v120, v119, v118
	v_fma_f32 v121, -v117, v120, v119
	v_fmac_f32_e32 v120, v121, v118
	v_fma_f32 v117, -v117, v120, v119
	v_div_fmas_f32 v117, v117, v118, v120
	v_div_fixup_f32 v120, v117, v116, 1.0
	v_lshl_add_u64 v[116:117], s[22:23], 0, v[122:123]
	v_pk_mul_f32 v[108:109], v[108:109], v[120:121] op_sel_hi:[1,0]
	v_pk_mul_f32 v[110:111], v[110:111], v[120:121] op_sel_hi:[1,0]
	v_pk_mul_f32 v[100:101], v[100:101], v[120:121] op_sel_hi:[1,0]
	v_pk_mul_f32 v[102:103], v[102:103], v[120:121] op_sel_hi:[1,0]
	v_lshlrev_b64 v[118:119], 8, v[116:117]
	v_pk_mul_f32 v[108:109], v[228:229], v[108:109]
	v_pk_mul_f32 v[110:111], v[230:231], v[110:111]
	v_cvt_pk_bf16_f32 v108, v108, v109
	s_nop 0
	v_cvt_pk_bf16_f32 v109, v110, v111
	v_cvt_pk_bf16_f32 v104, v104, v105
	v_cvt_pk_bf16_f32 v105, v106, v107
	v_pk_mul_f32 v[102:103], v[234:235], v[102:103]
	v_pk_mul_f32 v[100:101], v[232:233], v[100:101]
	s_nop 0
	v_cvt_pk_bf16_f32 v110, v100, v101
	v_cvt_pk_bf16_f32 v111, v102, v103
	v_cvt_pk_bf16_f32 v106, v96, v97
	v_mad_u64_u32 v[96:97], s[6:7], v116, s67, v[112:113]
	v_mad_i32_i24 v97, v117, s67, v97
	v_lshl_add_u64 v[96:97], v[96:97], 0, v[160:161]
	v_cvt_pk_bf16_f32 v107, v98, v99
	v_lshl_add_u64 v[98:99], s[68:69], 0, v[118:119]
	v_lshl_add_u64 v[96:97], v[96:97], 0, v[114:115]
	global_store_dwordx4 v[96:97], v[108:111], off
	v_lshl_add_u64 v[96:97], v[98:99], 0, v[160:161]
	v_lshl_add_u64 v[96:97], v[96:97], 0, v[114:115]
	global_store_dwordx4 v[96:97], v[104:107], off
	v_or_b32_e32 v102, 32, v149
	s_nop 0
	v_lshl_add_u32 v96, v102, 4, s24
	ds_read_b128 v[96:99], v96
	v_ashrrev_i32_e32 v103, 31, v102
	s_waitcnt lgkmcnt(0)
; #define PG8_LAS __attribute__((address_space(3)))
; __device__ __forceinline__ unsigned cvt_pk_bf16(float lo, float hi) { unsigned r; asm volatile("v_cvt_pk_bf16_f32 %0, %1, %2" : "=v"(r) : "v"(lo), "v"(hi)); return r; }
;     __device__ __forceinline__ void operator()(const f32x4 (&acc)[2][2][4][2], const Unit& u, int wr_, int wc_, int fr_, int fq_) const {
;     ...
;         for (int ai = 0; ai < 2; ++ai)
; #pragma unroll
;             for (int m = 0; m < 4; ++m) { int rl = ai * HALF + wr * 64 + m * 16 + fr; asm volatile("" : "+v"(rl));
;                 const f32x4 pp = *(const PG8_LAS f32x4*)(P + rl * 4);
;                 const float rr = 1.0f / sqrtf(((pp[0] + pp[1]) + (pp[2] + pp[3])) * (1.0f / 128.0f) + RMS_EPS_F);
;                 const size_t tok = (size_t)(b * 4 + u.pn) * 8192 + s0 + rl;
;                 bf16_t* krow = Kb + tok * 192; bf16_t* vrow = Vb + tok * 128;
;                 u32x4 w1, w2;
; #pragma unroll
;                 for (int n = 0; n < 2; ++n) { const f32x4 g = *(const f32x4*)(gn_k + wc * 32 + 8 * fq + 4 * n);
;                     const f32x4 kx = acc[ai][0][m][n] * rr * g, vx = acc[ai][1][m][n];
;                     w1[2 * n] = cvt_pk_bf16(kx[0], kx[1]); w1[2 * n + 1] = cvt_pk_bf16(kx[2], kx[3]); w2[2 * n] = cvt_pk_bf16(vx[0], vx[1]); w2[2 * n + 1] = cvt_pk_bf16(vx[2], vx[3]); }
;                 *(u32x4*)(krow + wc * 32 + 8 * fq) = w1; *(u32x4*)(vrow + wc * 32 + 8 * fq) = w2;
;                 asm volatile("" ::: "memory"); }
	v_mov_b32_e32 v100, v97
	v_mov_b32_e32 v101, v98
	v_mov_b32_e32 v97, v99
	v_pk_add_f32 v[96:97], v[100:101], v[96:97]
	s_nop 0
	v_add_f32_e32 v96, v96, v97
	v_fmamk_f32 v96, v96, 0x3c000000, v199
	v_cmp_gt_f32_e32 vcc, s25, v96
	v_mul_f32_e32 v97, 0x4f800000, v96
	s_nop 0
	v_cndmask_b32_e32 v96, v96, v97, vcc
	v_sqrt_f32_e32 v97, v96
	s_nop 0
	v_add_u32_e32 v98, -1, v97
	v_fma_f32 v99, -v98, v97, v96
	v_cmp_ge_f32_e64 s[6:7], 0, v99
	v_add_u32_e32 v99, 1, v97
	s_nop 0
	v_cndmask_b32_e64 v98, v97, v98, s[6:7]
	v_fma_f32 v97, -v99, v97, v96
	v_cmp_lt_f32_e64 s[6:7], 0, v97
	s_nop 1
	v_cndmask_b32_e64 v97, v98, v99, s[6:7]
	v_mul_f32_e32 v98, 0x37800000, v97
	v_cndmask_b32_e32 v97, v97, v98, vcc
	v_cmp_class_f32_e32 vcc, v96, v201
	s_nop 1
	v_cndmask_b32_e32 v96, v97, v96, vcc
	v_div_scale_f32 v97, s[6:7], v96, v96, 1.0
	v_rcp_f32_e32 v98, v97
	s_nop 0
	v_fma_f32 v99, -v97, v98, 1.0
	v_fmac_f32_e32 v98, v99, v98
	v_div_scale_f32 v99, vcc, 1.0, v96, 1.0
	v_mul_f32_e32 v100, v99, v98
	v_fma_f32 v101, -v97, v100, v99
	v_fmac_f32_e32 v100, v101, v98
	v_fma_f32 v97, -v97, v100, v99
	v_div_fmas_f32 v97, v97, v98, v100
	v_div_fixup_f32 v100, v97, v96, 1.0
	v_lshl_add_u64 v[96:97], s[22:23], 0, v[102:103]
	v_pk_mul_f32 v[92:93], v[92:93], v[100:101] op_sel_hi:[1,0]
	v_pk_mul_f32 v[94:95], v[94:95], v[100:101] op_sel_hi:[1,0]
	v_pk_mul_f32 v[84:85], v[84:85], v[100:101] op_sel_hi:[1,0]
	v_pk_mul_f32 v[86:87], v[86:87], v[100:101] op_sel_hi:[1,0]
	v_lshlrev_b64 v[98:99], 8, v[96:97]
	v_pk_mul_f32 v[92:93], v[228:229], v[92:93]
	v_pk_mul_f32 v[94:95], v[230:231], v[94:95]
	v_cvt_pk_bf16_f32 v92, v92, v93
	s_nop 0
	v_cvt_pk_bf16_f32 v93, v94, v95
	v_cvt_pk_bf16_f32 v88, v88, v89
	v_cvt_pk_bf16_f32 v89, v90, v91
	v_pk_mul_f32 v[86:87], v[234:235], v[86:87]
	v_pk_mul_f32 v[84:85], v[232:233], v[84:85]
	s_nop 0
	v_cvt_pk_bf16_f32 v94, v84, v85
	v_cvt_pk_bf16_f32 v95, v86, v87
	v_cvt_pk_bf16_f32 v90, v80, v81
	v_mad_u64_u32 v[80:81], s[6:7], v96, s67, v[112:113]
	v_mad_i32_i24 v81, v97, s67, v81
	v_lshl_add_u64 v[80:81], v[80:81], 0, v[160:161]
	v_cvt_pk_bf16_f32 v91, v82, v83
	v_lshl_add_u64 v[82:83], s[68:69], 0, v[98:99]
	v_lshl_add_u64 v[80:81], v[80:81], 0, v[114:115]
	global_store_dwordx4 v[80:81], v[92:95], off
	v_lshl_add_u64 v[80:81], v[82:83], 0, v[160:161]
	v_lshl_add_u64 v[80:81], v[80:81], 0, v[114:115]
	global_store_dwordx4 v[80:81], v[88:91], off
	v_or_b32_e32 v86, 48, v149
	s_nop 0
	v_lshl_add_u32 v80, v86, 4, s24
	ds_read_b128 v[80:83], v80
	v_ashrrev_i32_e32 v87, 31, v86
	s_waitcnt lgkmcnt(0)
	v_mov_b32_e32 v84, v81
	v_mov_b32_e32 v85, v82
	v_mov_b32_e32 v81, v83
	v_pk_add_f32 v[80:81], v[84:85], v[80:81]
	s_nop 0
	v_add_f32_e32 v80, v80, v81
	v_fmamk_f32 v80, v80, 0x3c000000, v199
	v_cmp_gt_f32_e32 vcc, s25, v80
	v_mul_f32_e32 v81, 0x4f800000, v80
	s_nop 0
	v_cndmask_b32_e32 v80, v80, v81, vcc
	v_sqrt_f32_e32 v81, v80
	s_nop 0
	v_add_u32_e32 v82, -1, v81
	v_fma_f32 v83, -v82, v81, v80
	v_cmp_ge_f32_e64 s[6:7], 0, v83
	v_add_u32_e32 v83, 1, v81
	s_nop 0
	v_cndmask_b32_e64 v82, v81, v82, s[6:7]
	v_fma_f32 v81, -v83, v81, v80
	v_cmp_lt_f32_e64 s[6:7], 0, v81
	s_nop 1
	v_cndmask_b32_e64 v81, v82, v83, s[6:7]
	v_mul_f32_e32 v82, 0x37800000, v81
	v_cndmask_b32_e32 v81, v81, v82, vcc
	v_cmp_class_f32_e32 vcc, v80, v201
	s_nop 1
	v_cndmask_b32_e32 v80, v81, v80, vcc
	v_div_scale_f32 v81, s[6:7], v80, v80, 1.0
	v_rcp_f32_e32 v82, v81
	s_nop 0
	v_fma_f32 v83, -v81, v82, 1.0
	v_fmac_f32_e32 v82, v83, v82
	v_div_scale_f32 v83, vcc, 1.0, v80, 1.0
	v_mul_f32_e32 v84, v83, v82
	v_fma_f32 v85, -v81, v84, v83
	v_fmac_f32_e32 v84, v85, v82
	v_fma_f32 v81, -v81, v84, v83
	v_div_fmas_f32 v81, v81, v82, v84
	v_div_fixup_f32 v84, v81, v80, 1.0
	v_lshl_add_u64 v[80:81], s[22:23], 0, v[86:87]
	v_pk_mul_f32 v[76:77], v[76:77], v[84:85] op_sel_hi:[1,0]
	v_pk_mul_f32 v[78:79], v[78:79], v[84:85] op_sel_hi:[1,0]
	v_pk_mul_f32 v[68:69], v[68:69], v[84:85] op_sel_hi:[1,0]
	v_pk_mul_f32 v[70:71], v[70:71], v[84:85] op_sel_hi:[1,0]
	v_lshlrev_b64 v[82:83], 8, v[80:81]
	v_pk_mul_f32 v[76:77], v[228:229], v[76:77]
	v_pk_mul_f32 v[78:79], v[230:231], v[78:79]
	v_cvt_pk_bf16_f32 v76, v76, v77
	s_nop 0
	v_cvt_pk_bf16_f32 v77, v78, v79
	v_cvt_pk_bf16_f32 v72, v72, v73
	v_cvt_pk_bf16_f32 v73, v74, v75
	v_pk_mul_f32 v[70:71], v[234:235], v[70:71]
	v_pk_mul_f32 v[68:69], v[232:233], v[68:69]
	s_nop 0
	v_cvt_pk_bf16_f32 v78, v68, v69
	v_cvt_pk_bf16_f32 v79, v70, v71
	v_cvt_pk_bf16_f32 v74, v64, v65
	v_mad_u64_u32 v[64:65], s[6:7], v80, s67, v[112:113]
	v_mad_i32_i24 v65, v81, s67, v65
	v_lshl_add_u64 v[64:65], v[64:65], 0, v[160:161]
	v_cvt_pk_bf16_f32 v75, v66, v67
	v_lshl_add_u64 v[66:67], s[68:69], 0, v[82:83]
	v_lshl_add_u64 v[64:65], v[64:65], 0, v[114:115]
	global_store_dwordx4 v[64:65], v[76:79], off
	v_lshl_add_u64 v[64:65], v[66:67], 0, v[160:161]
	v_lshl_add_u64 v[64:65], v[64:65], 0, v[114:115]
	global_store_dwordx4 v[64:65], v[72:75], off
	v_add_u32_e32 v70, 0x80, v149
	s_nop 0
	v_lshl_add_u32 v64, v70, 4, s24
	ds_read_b128 v[64:67], v64
	v_ashrrev_i32_e32 v71, 31, v70
	s_waitcnt lgkmcnt(0)
; #define PG8_LAS __attribute__((address_space(3)))
; __device__ __forceinline__ unsigned cvt_pk_bf16(float lo, float hi) { unsigned r; asm volatile("v_cvt_pk_bf16_f32 %0, %1, %2" : "=v"(r) : "v"(lo), "v"(hi)); return r; }
;     __device__ __forceinline__ void operator()(const f32x4 (&acc)[2][2][4][2], const Unit& u, int wr_, int wc_, int fr_, int fq_) const {
;     ...
;         for (int ai = 0; ai < 2; ++ai)
; #pragma unroll
;             for (int m = 0; m < 4; ++m) { int rl = ai * HALF + wr * 64 + m * 16 + fr; asm volatile("" : "+v"(rl));
;                 const f32x4 pp = *(const PG8_LAS f32x4*)(P + rl * 4);
;                 const float rr = 1.0f / sqrtf(((pp[0] + pp[1]) + (pp[2] + pp[3])) * (1.0f / 128.0f) + RMS_EPS_F);
;                 const size_t tok = (size_t)(b * 4 + u.pn) * 8192 + s0 + rl;
;                 bf16_t* krow = Kb + tok * 192; bf16_t* vrow = Vb + tok * 128;
;                 u32x4 w1, w2;
; #pragma unroll
;                 for (int n = 0; n < 2; ++n) { const f32x4 g = *(const f32x4*)(gn_k + wc * 32 + 8 * fq + 4 * n);
;                     const f32x4 kx = acc[ai][0][m][n] * rr * g, vx = acc[ai][1][m][n];
;                     w1[2 * n] = cvt_pk_bf16(kx[0], kx[1]); w1[2 * n + 1] = cvt_pk_bf16(kx[2], kx[3]); w2[2 * n] = cvt_pk_bf16(vx[0], vx[1]); w2[2 * n + 1] = cvt_pk_bf16(vx[2], vx[3]); }
;                 *(u32x4*)(krow + wc * 32 + 8 * fq) = w1; *(u32x4*)(vrow + wc * 32 + 8 * fq) = w2;
;                 asm volatile("" ::: "memory"); }
	v_mov_b32_e32 v68, v65
	v_mov_b32_e32 v69, v66
	v_mov_b32_e32 v65, v67
	v_pk_add_f32 v[64:65], v[68:69], v[64:65]
	s_nop 0
	v_add_f32_e32 v64, v64, v65
	v_fmamk_f32 v64, v64, 0x3c000000, v199
	v_cmp_gt_f32_e32 vcc, s25, v64
	v_mul_f32_e32 v65, 0x4f800000, v64
	s_nop 0
	v_cndmask_b32_e32 v64, v64, v65, vcc
	v_sqrt_f32_e32 v65, v64
	s_nop 0
	v_add_u32_e32 v66, -1, v65
	v_fma_f32 v67, -v66, v65, v64
	v_cmp_ge_f32_e64 s[6:7], 0, v67
	v_add_u32_e32 v67, 1, v65
	s_nop 0
	v_cndmask_b32_e64 v66, v65, v66, s[6:7]
	v_fma_f32 v65, -v67, v65, v64
	v_cmp_lt_f32_e64 s[6:7], 0, v65
	s_nop 1
	v_cndmask_b32_e64 v65, v66, v67, s[6:7]
	v_mul_f32_e32 v66, 0x37800000, v65
	v_cndmask_b32_e32 v65, v65, v66, vcc
	v_cmp_class_f32_e32 vcc, v64, v201
	s_nop 1
	v_cndmask_b32_e32 v64, v65, v64, vcc
	v_div_scale_f32 v65, s[6:7], v64, v64, 1.0
	v_rcp_f32_e32 v66, v65
	s_nop 0
	v_fma_f32 v67, -v65, v66, 1.0
	v_fmac_f32_e32 v66, v67, v66
	v_div_scale_f32 v67, vcc, 1.0, v64, 1.0
	v_mul_f32_e32 v68, v67, v66
	v_fma_f32 v69, -v65, v68, v67
	v_fmac_f32_e32 v68, v69, v66
	v_fma_f32 v65, -v65, v68, v67
	v_div_fmas_f32 v65, v65, v66, v68
	v_div_fixup_f32 v68, v65, v64, 1.0
	v_lshl_add_u64 v[64:65], s[22:23], 0, v[70:71]
	v_pk_mul_f32 v[60:61], v[60:61], v[68:69] op_sel_hi:[1,0]
	v_pk_mul_f32 v[62:63], v[62:63], v[68:69] op_sel_hi:[1,0]
	v_pk_mul_f32 v[52:53], v[52:53], v[68:69] op_sel_hi:[1,0]
	v_pk_mul_f32 v[54:55], v[54:55], v[68:69] op_sel_hi:[1,0]
	v_lshlrev_b64 v[66:67], 8, v[64:65]
	v_pk_mul_f32 v[60:61], v[228:229], v[60:61]
	v_pk_mul_f32 v[62:63], v[230:231], v[62:63]
	v_cvt_pk_bf16_f32 v60, v60, v61
	s_nop 0
	v_cvt_pk_bf16_f32 v61, v62, v63
	v_cvt_pk_bf16_f32 v56, v56, v57
	v_cvt_pk_bf16_f32 v57, v58, v59
	v_pk_mul_f32 v[54:55], v[234:235], v[54:55]
	v_pk_mul_f32 v[52:53], v[232:233], v[52:53]
	s_nop 0
	v_cvt_pk_bf16_f32 v62, v52, v53
	v_cvt_pk_bf16_f32 v63, v54, v55
	v_cvt_pk_bf16_f32 v58, v48, v49
	v_mad_u64_u32 v[48:49], s[6:7], v64, s67, v[112:113]
	v_mad_i32_i24 v49, v65, s67, v49
	v_lshl_add_u64 v[48:49], v[48:49], 0, v[160:161]
	v_cvt_pk_bf16_f32 v59, v50, v51
	v_lshl_add_u64 v[50:51], s[68:69], 0, v[66:67]
	v_lshl_add_u64 v[48:49], v[48:49], 0, v[114:115]
	global_store_dwordx4 v[48:49], v[60:63], off
	v_lshl_add_u64 v[48:49], v[50:51], 0, v[160:161]
	v_lshl_add_u64 v[48:49], v[48:49], 0, v[114:115]
	global_store_dwordx4 v[48:49], v[56:59], off
	v_add_u32_e32 v54, 0x90, v149
	s_nop 0
	v_lshl_add_u32 v48, v54, 4, s24
	ds_read_b128 v[48:51], v48
	v_ashrrev_i32_e32 v55, 31, v54
	s_waitcnt lgkmcnt(0)
	v_mov_b32_e32 v52, v49
	v_mov_b32_e32 v53, v50
	v_mov_b32_e32 v49, v51
	v_pk_add_f32 v[48:49], v[52:53], v[48:49]
	s_nop 0
	v_add_f32_e32 v48, v48, v49
	v_fmamk_f32 v48, v48, 0x3c000000, v199
	v_cmp_gt_f32_e32 vcc, s25, v48
	v_mul_f32_e32 v49, 0x4f800000, v48
	s_nop 0
	v_cndmask_b32_e32 v48, v48, v49, vcc
	v_sqrt_f32_e32 v49, v48
	s_nop 0
	v_add_u32_e32 v50, -1, v49
	v_fma_f32 v51, -v50, v49, v48
	v_cmp_ge_f32_e64 s[6:7], 0, v51
	v_add_u32_e32 v51, 1, v49
	s_nop 0
	v_cndmask_b32_e64 v50, v49, v50, s[6:7]
	v_fma_f32 v49, -v51, v49, v48
	v_cmp_lt_f32_e64 s[6:7], 0, v49
	s_nop 1
	v_cndmask_b32_e64 v49, v50, v51, s[6:7]
	v_mul_f32_e32 v50, 0x37800000, v49
	v_cndmask_b32_e32 v49, v49, v50, vcc
	v_cmp_class_f32_e32 vcc, v48, v201
	s_nop 1
	v_cndmask_b32_e32 v48, v49, v48, vcc
	v_div_scale_f32 v49, s[6:7], v48, v48, 1.0
	v_rcp_f32_e32 v50, v49
	s_nop 0
	v_fma_f32 v51, -v49, v50, 1.0
	v_fmac_f32_e32 v50, v51, v50
	v_div_scale_f32 v51, vcc, 1.0, v48, 1.0
	v_mul_f32_e32 v52, v51, v50
	v_fma_f32 v53, -v49, v52, v51
	v_fmac_f32_e32 v52, v53, v50
	v_fma_f32 v49, -v49, v52, v51
	v_div_fmas_f32 v49, v49, v50, v52
	v_div_fixup_f32 v52, v49, v48, 1.0
	v_lshl_add_u64 v[48:49], s[22:23], 0, v[54:55]
	v_pk_mul_f32 v[44:45], v[44:45], v[52:53] op_sel_hi:[1,0]
	v_pk_mul_f32 v[46:47], v[46:47], v[52:53] op_sel_hi:[1,0]
	v_pk_mul_f32 v[36:37], v[36:37], v[52:53] op_sel_hi:[1,0]
	v_pk_mul_f32 v[38:39], v[38:39], v[52:53] op_sel_hi:[1,0]
	v_lshlrev_b64 v[50:51], 8, v[48:49]
	v_pk_mul_f32 v[44:45], v[228:229], v[44:45]
	v_pk_mul_f32 v[46:47], v[230:231], v[46:47]
	v_cvt_pk_bf16_f32 v44, v44, v45
	s_nop 0
	v_cvt_pk_bf16_f32 v45, v46, v47
	v_cvt_pk_bf16_f32 v40, v40, v41
	v_cvt_pk_bf16_f32 v41, v42, v43
	v_pk_mul_f32 v[38:39], v[234:235], v[38:39]
	v_pk_mul_f32 v[36:37], v[232:233], v[36:37]
	s_nop 0
	v_cvt_pk_bf16_f32 v46, v36, v37
	v_cvt_pk_bf16_f32 v47, v38, v39
	v_cvt_pk_bf16_f32 v42, v32, v33
	v_mad_u64_u32 v[32:33], s[6:7], v48, s67, v[112:113]
	v_mad_i32_i24 v33, v49, s67, v33
	v_lshl_add_u64 v[32:33], v[32:33], 0, v[160:161]
	v_cvt_pk_bf16_f32 v43, v34, v35
	v_lshl_add_u64 v[34:35], s[68:69], 0, v[50:51]
	v_lshl_add_u64 v[32:33], v[32:33], 0, v[114:115]
	global_store_dwordx4 v[32:33], v[44:47], off
	v_lshl_add_u64 v[32:33], v[34:35], 0, v[160:161]
	v_lshl_add_u64 v[32:33], v[32:33], 0, v[114:115]
	global_store_dwordx4 v[32:33], v[40:43], off
	v_add_u32_e32 v38, 0xa0, v149
	s_nop 0
	v_lshl_add_u32 v32, v38, 4, s24
	ds_read_b128 v[32:35], v32
	v_ashrrev_i32_e32 v39, 31, v38
	s_waitcnt lgkmcnt(0)
; #define PG8_LAS __attribute__((address_space(3)))
; __device__ __forceinline__ unsigned cvt_pk_bf16(float lo, float hi) { unsigned r; asm volatile("v_cvt_pk_bf16_f32 %0, %1, %2" : "=v"(r) : "v"(lo), "v"(hi)); return r; }
; #define PG8_BAR __builtin_amdgcn_s_barrier()
; template <class Epi, class Sched, bool ALIGN_EPI = false, bool SP2 = false>
; __device__ __forceinline__ void gemm_phase(PG8_LAS unsigned char* lds, const Gemm g, const Sched& S, const Epi& E) {
;     ...
;         if (!has_next) break;
; #pragma unroll
;         for (int a = 0; a < 2; ++a)
; #pragma unroll
;             for (int b = 0; b < 2; ++b)
; #pragma unroll
;                 for (int m = 0; m < 4; ++m)
; #pragma unroll
;                     for (int n = 0; n < 2; ++n) acc[a][b][m][n] = (f32x4){0.f, 0.f, 0.f, 0.f};
;         cur = nxt; cA = nA; cB = nB; ++ui;
;         if constexpr (ALIGN_EPI) { if (wr == 1) PG8_BAR; }
;     __device__ __forceinline__ void operator()(const f32x4 (&acc)[2][2][4][2], const Unit& u, int wr_, int wc_, int fr_, int fq_) const {
;     ...
;         for (int ai = 0; ai < 2; ++ai)
; #pragma unroll
;             for (int m = 0; m < 4; ++m) { int rl = ai * HALF + wr * 64 + m * 16 + fr; asm volatile("" : "+v"(rl));
;                 const f32x4 pp = *(const PG8_LAS f32x4*)(P + rl * 4);
;                 const float rr = 1.0f / sqrtf(((pp[0] + pp[1]) + (pp[2] + pp[3])) * (1.0f / 128.0f) + RMS_EPS_F);
;                 const size_t tok = (size_t)(b * 4 + u.pn) * 8192 + s0 + rl;
;                 bf16_t* krow = Kb + tok * 192; bf16_t* vrow = Vb + tok * 128;
;                 u32x4 w1, w2;
; #pragma unroll
;                 for (int n = 0; n < 2; ++n) { const f32x4 g = *(const f32x4*)(gn_k + wc * 32 + 8 * fq + 4 * n);
;                     const f32x4 kx = acc[ai][0][m][n] * rr * g, vx = acc[ai][1][m][n];
;                     w1[2 * n] = cvt_pk_bf16(kx[0], kx[1]); w1[2 * n + 1] = cvt_pk_bf16(kx[2], kx[3]); w2[2 * n] = cvt_pk_bf16(vx[0], vx[1]); w2[2 * n + 1] = cvt_pk_bf16(vx[2], vx[3]); }
;                 *(u32x4*)(krow + wc * 32 + 8 * fq) = w1; *(u32x4*)(vrow + wc * 32 + 8 * fq) = w2;
;                 asm volatile("" ::: "memory"); }
	v_mov_b32_e32 v36, v33
	v_mov_b32_e32 v37, v34
	v_mov_b32_e32 v33, v35
	v_pk_add_f32 v[32:33], v[36:37], v[32:33]
	s_nop 0
	v_add_f32_e32 v32, v32, v33
	v_fmamk_f32 v32, v32, 0x3c000000, v199
	v_cmp_gt_f32_e32 vcc, s25, v32
	v_mul_f32_e32 v33, 0x4f800000, v32
	s_nop 0
	v_cndmask_b32_e32 v32, v32, v33, vcc
	v_sqrt_f32_e32 v33, v32
	s_nop 0
	v_add_u32_e32 v34, -1, v33
	v_fma_f32 v35, -v34, v33, v32
	v_cmp_ge_f32_e64 s[6:7], 0, v35
	v_add_u32_e32 v35, 1, v33
	s_nop 0
	v_cndmask_b32_e64 v34, v33, v34, s[6:7]
	v_fma_f32 v33, -v35, v33, v32
	v_cmp_lt_f32_e64 s[6:7], 0, v33
	s_nop 1
	v_cndmask_b32_e64 v33, v34, v35, s[6:7]
	v_mul_f32_e32 v34, 0x37800000, v33
	v_cndmask_b32_e32 v33, v33, v34, vcc
	v_cmp_class_f32_e32 vcc, v32, v201
	s_nop 1
	v_cndmask_b32_e32 v32, v33, v32, vcc
	v_div_scale_f32 v33, s[6:7], v32, v32, 1.0
	v_rcp_f32_e32 v34, v33
	s_nop 0
	v_fma_f32 v35, -v33, v34, 1.0
	v_fmac_f32_e32 v34, v35, v34
	v_div_scale_f32 v35, vcc, 1.0, v32, 1.0
	v_mul_f32_e32 v36, v35, v34
	v_fma_f32 v37, -v33, v36, v35
	v_fmac_f32_e32 v36, v37, v34
	v_fma_f32 v33, -v33, v36, v35
	v_div_fmas_f32 v33, v33, v34, v36
	v_div_fixup_f32 v36, v33, v32, 1.0
	v_lshl_add_u64 v[32:33], s[22:23], 0, v[38:39]
	v_pk_mul_f32 v[28:29], v[28:29], v[36:37] op_sel_hi:[1,0]
	v_pk_mul_f32 v[30:31], v[30:31], v[36:37] op_sel_hi:[1,0]
	v_pk_mul_f32 v[20:21], v[20:21], v[36:37] op_sel_hi:[1,0]
	v_pk_mul_f32 v[22:23], v[22:23], v[36:37] op_sel_hi:[1,0]
	v_lshlrev_b64 v[34:35], 8, v[32:33]
	v_pk_mul_f32 v[28:29], v[228:229], v[28:29]
	v_pk_mul_f32 v[30:31], v[230:231], v[30:31]
	v_cvt_pk_bf16_f32 v28, v28, v29
	s_nop 0
	v_cvt_pk_bf16_f32 v29, v30, v31
	v_cvt_pk_bf16_f32 v24, v24, v25
	v_cvt_pk_bf16_f32 v25, v26, v27
	v_pk_mul_f32 v[22:23], v[234:235], v[22:23]
	v_pk_mul_f32 v[20:21], v[232:233], v[20:21]
	s_nop 0
	v_cvt_pk_bf16_f32 v30, v20, v21
	v_cvt_pk_bf16_f32 v31, v22, v23
	v_cvt_pk_bf16_f32 v26, v16, v17
	v_mad_u64_u32 v[16:17], s[6:7], v32, s67, v[112:113]
	v_mad_i32_i24 v17, v33, s67, v17
	v_lshl_add_u64 v[16:17], v[16:17], 0, v[160:161]
	v_cvt_pk_bf16_f32 v27, v18, v19
	v_lshl_add_u64 v[18:19], s[68:69], 0, v[34:35]
	v_lshl_add_u64 v[16:17], v[16:17], 0, v[114:115]
	global_store_dwordx4 v[16:17], v[28:31], off
	v_lshl_add_u64 v[16:17], v[18:19], 0, v[160:161]
	v_lshl_add_u64 v[16:17], v[16:17], 0, v[114:115]
	global_store_dwordx4 v[16:17], v[24:27], off
	v_add_u32_e32 v22, 0xb0, v149
	s_nop 0
	v_lshl_add_u32 v16, v22, 4, s24
	ds_read_b128 v[16:19], v16
	v_ashrrev_i32_e32 v23, 31, v22
	s_waitcnt lgkmcnt(0)
	v_mov_b32_e32 v20, v17
	v_mov_b32_e32 v21, v18
	v_mov_b32_e32 v17, v19
	v_pk_add_f32 v[16:17], v[20:21], v[16:17]
	s_nop 0
	v_add_f32_e32 v16, v16, v17
	v_fmamk_f32 v16, v16, 0x3c000000, v199
	v_cmp_gt_f32_e32 vcc, s25, v16
	v_mul_f32_e32 v17, 0x4f800000, v16
	s_nop 0
	v_cndmask_b32_e32 v16, v16, v17, vcc
	v_sqrt_f32_e32 v17, v16
	s_nop 0
	v_add_u32_e32 v18, -1, v17
	v_fma_f32 v19, -v18, v17, v16
	v_cmp_ge_f32_e64 s[6:7], 0, v19
	v_add_u32_e32 v19, 1, v17
	s_nop 0
	v_cndmask_b32_e64 v18, v17, v18, s[6:7]
	v_fma_f32 v17, -v19, v17, v16
	v_cmp_lt_f32_e64 s[6:7], 0, v17
	s_nop 1
	v_cndmask_b32_e64 v17, v18, v19, s[6:7]
	v_mul_f32_e32 v18, 0x37800000, v17
	v_cndmask_b32_e32 v17, v17, v18, vcc
	v_cmp_class_f32_e32 vcc, v16, v201
	s_nop 1
	v_cndmask_b32_e32 v16, v17, v16, vcc
	v_div_scale_f32 v17, s[6:7], v16, v16, 1.0
	v_rcp_f32_e32 v18, v17
	s_nop 0
	v_fma_f32 v19, -v17, v18, 1.0
	v_fmac_f32_e32 v18, v19, v18
	v_div_scale_f32 v19, vcc, 1.0, v16, 1.0
	v_mul_f32_e32 v20, v19, v18
	v_fma_f32 v21, -v17, v20, v19
	v_fmac_f32_e32 v20, v21, v18
	v_fma_f32 v17, -v17, v20, v19
	v_div_fmas_f32 v17, v17, v18, v20
	v_lshl_add_u64 v[18:19], s[22:23], 0, v[22:23]
	v_div_fixup_f32 v20, v17, v16, 1.0
	v_pk_mul_f32 v[12:13], v[12:13], v[20:21] op_sel_hi:[1,0]
	v_pk_mul_f32 v[14:15], v[14:15], v[20:21] op_sel_hi:[1,0]
	v_pk_mul_f32 v[4:5], v[4:5], v[20:21] op_sel_hi:[1,0]
	v_pk_mul_f32 v[6:7], v[6:7], v[20:21] op_sel_hi:[1,0]
	v_lshlrev_b64 v[16:17], 8, v[18:19]
	s_and_b64 vcc, exec, s[0:1]
	v_pk_mul_f32 v[12:13], v[228:229], v[12:13]
	v_pk_mul_f32 v[14:15], v[230:231], v[14:15]
	v_cvt_pk_bf16_f32 v12, v12, v13
	s_nop 0
	v_cvt_pk_bf16_f32 v13, v14, v15
	v_cvt_pk_bf16_f32 v8, v8, v9
	v_cvt_pk_bf16_f32 v9, v10, v11
	v_pk_mul_f32 v[6:7], v[234:235], v[6:7]
	v_pk_mul_f32 v[4:5], v[232:233], v[4:5]
	s_nop 0
	v_cvt_pk_bf16_f32 v14, v4, v5
	v_cvt_pk_bf16_f32 v15, v6, v7
	v_cvt_pk_bf16_f32 v10, v0, v1
	v_mad_u64_u32 v[0:1], s[6:7], v18, s67, v[112:113]
	v_mad_i32_i24 v1, v19, s67, v1
	v_lshl_add_u64 v[0:1], v[0:1], 0, v[160:161]
	v_cvt_pk_bf16_f32 v11, v2, v3
	v_lshl_add_u64 v[2:3], s[68:69], 0, v[16:17]
	v_lshl_add_u64 v[0:1], v[0:1], 0, v[114:115]
	global_store_dwordx4 v[0:1], v[12:15], off
	v_lshl_add_u64 v[0:1], v[2:3], 0, v[160:161]
	v_lshl_add_u64 v[0:1], v[0:1], 0, v[114:115]
	global_store_dwordx4 v[0:1], v[8:11], off
	s_mov_b64 s[6:7], -1
	s_cbranch_vccnz .LBB0_441
	s_andn2_b64 vcc, exec, s[10:11]
	s_cbranch_vccnz .LBB0_440
	s_barrier
	s_branch .LBB0_440
